# stack42 with the static raise for waves 4-7 kept for the rest of the kernel (no s_setprio 0 resets after the GEMM loops)
# baseline (speedup 1.0000x reference)
.Lgprio0:
.LBB0_159:
	ds_read_b128 v[150:153], v147
	ds_read_b128 v[154:157], v147 offset:1024
	ds_read_b128 v[158:161], v147 offset:2048
	ds_read_b128 v[162:165], v147 offset:3072
	ds_read_b128 v[166:169], v148
	ds_read_b128 v[170:173], v148 offset:1024
	ds_read_b128 v[174:177], v148 offset:2048
	ds_read_b128 v[178:181], v148 offset:3072
	s_add_u32 s38, s36, 0x100
	s_addc_u32 s39, s37, 0
	s_cmp_eq_u32 s59, 28
	s_cselect_b32 s43, s19, s39
	s_cselect_b32 s42, s55, s38
	s_cselect_b32 s41, s17, s58
	s_cselect_b32 s40, s56, s57
	v_lshl_add_u64 v[182:183], s[36:37], 0, v[136:137]
	s_add_i32 m0, s35, 0xc000
	s_nop 0
	global_load_lds_dwordx4 v[182:183], off
	v_lshl_add_u64 v[182:183], s[36:37], 0, v[138:139]
	s_add_i32 m0, s35, 0xe000
	s_nop 0
	global_load_lds_dwordx4 v[182:183], off
	ds_read_b128 v[182:185], v149
	ds_read_b128 v[186:189], v149 offset:1024
	ds_read_b128 v[190:193], v149 offset:2048
	ds_read_b128 v[194:197], v149 offset:3072
	ds_read_b128 v[198:201], v149 offset:4096
	ds_read_b128 v[202:205], v149 offset:5120
	ds_read_b128 v[206:209], v149 offset:6144
	ds_read_b128 v[210:213], v149 offset:7168
	s_waitcnt vmcnt(8)
	s_waitcnt lgkmcnt(0)
	s_barrier
	s_waitcnt lgkmcnt(0)
	v_mfma_f32_16x16x32_bf16 v[124:127], v[150:153], v[182:185], v[124:127]
	v_mfma_f32_16x16x32_bf16 v[120:123], v[158:161], v[182:185], v[120:123]
	v_mfma_f32_16x16x32_bf16 v[108:111], v[150:153], v[190:193], v[108:111]
	v_mfma_f32_16x16x32_bf16 v[104:107], v[158:161], v[190:193], v[104:107]
	v_mfma_f32_16x16x32_bf16 v[92:95], v[150:153], v[198:201], v[92:95]
	v_mfma_f32_16x16x32_bf16 v[88:91], v[158:161], v[198:201], v[88:91]
	v_mfma_f32_16x16x32_bf16 v[76:79], v[150:153], v[206:209], v[76:79]
	v_mfma_f32_16x16x32_bf16 v[72:75], v[158:161], v[206:209], v[72:75]
	v_mfma_f32_16x16x32_bf16 v[124:127], v[154:157], v[186:189], v[124:127]
	v_mfma_f32_16x16x32_bf16 v[120:123], v[162:165], v[186:189], v[120:123]
	v_mfma_f32_16x16x32_bf16 v[108:111], v[154:157], v[194:197], v[108:111]
	v_mfma_f32_16x16x32_bf16 v[104:107], v[162:165], v[194:197], v[104:107]
	v_mfma_f32_16x16x32_bf16 v[92:95], v[154:157], v[202:205], v[92:95]
	v_mfma_f32_16x16x32_bf16 v[88:91], v[162:165], v[202:205], v[88:91]
	v_mfma_f32_16x16x32_bf16 v[76:79], v[154:157], v[210:213], v[76:79]
	v_mfma_f32_16x16x32_bf16 v[72:75], v[162:165], v[210:213], v[72:75]
	v_mfma_f32_16x16x32_bf16 v[116:119], v[166:169], v[182:185], v[116:119]
	v_mfma_f32_16x16x32_bf16 v[112:115], v[174:177], v[182:185], v[112:115]
	v_mfma_f32_16x16x32_bf16 v[100:103], v[166:169], v[190:193], v[100:103]
	v_mfma_f32_16x16x32_bf16 v[96:99], v[174:177], v[190:193], v[96:99]
	v_mfma_f32_16x16x32_bf16 v[84:87], v[166:169], v[198:201], v[84:87]
	v_mfma_f32_16x16x32_bf16 v[80:83], v[174:177], v[198:201], v[80:83]
	v_mfma_f32_16x16x32_bf16 v[68:71], v[166:169], v[206:209], v[68:71]
	v_mfma_f32_16x16x32_bf16 v[64:67], v[174:177], v[206:209], v[64:67]
	v_mfma_f32_16x16x32_bf16 v[116:119], v[170:173], v[186:189], v[116:119]
	v_mfma_f32_16x16x32_bf16 v[112:115], v[178:181], v[186:189], v[112:115]
	v_mfma_f32_16x16x32_bf16 v[100:103], v[170:173], v[194:197], v[100:103]
	v_mfma_f32_16x16x32_bf16 v[96:99], v[178:181], v[194:197], v[96:99]
	v_mfma_f32_16x16x32_bf16 v[84:87], v[170:173], v[202:205], v[84:87]
	v_mfma_f32_16x16x32_bf16 v[80:83], v[178:181], v[202:205], v[80:83]
	v_mfma_f32_16x16x32_bf16 v[68:71], v[170:173], v[210:213], v[68:71]
	v_mfma_f32_16x16x32_bf16 v[64:67], v[178:181], v[210:213], v[64:67]
	s_barrier
	s_add_i32 s36, s51, s11
	v_lshl_add_u64 v[214:215], s[40:41], 0, v[130:131]
	s_mov_b32 m0, s36
	v_lshl_add_u64 v[216:217], s[40:41], 0, v[134:135]
	global_load_lds_dwordx4 v[214:215], off
	s_add_i32 m0, s36, 0x2000
	s_add_u32 s36, s40, 0x80000
	s_addc_u32 s37, s41, 0
	s_add_i32 s60, s52, s11
	global_load_lds_dwordx4 v[216:217], off
	v_lshl_add_u64 v[182:183], s[36:37], 0, v[130:131]
	s_mov_b32 m0, s60
	v_lshl_add_u64 v[218:219], s[42:43], 0, v[128:129]
	global_load_lds_dwordx4 v[182:183], off
	v_lshl_add_u64 v[182:183], s[36:37], 0, v[134:135]
	s_add_i32 m0, s60, 0x2000
	v_lshl_add_u64 v[220:221], s[42:43], 0, v[132:133]
	global_load_lds_dwordx4 v[182:183], off
	s_mov_b32 m0, s35
	s_nop 0
	global_load_lds_dwordx4 v[218:219], off
	s_mov_b32 m0, s44
	s_nop 0
	global_load_lds_dwordx4 v[220:221], off
	ds_read_b128 v[182:185], v149 offset:16384
	ds_read_b128 v[186:189], v149 offset:17408
	ds_read_b128 v[190:193], v149 offset:18432
	ds_read_b128 v[194:197], v149 offset:19456
	ds_read_b128 v[198:201], v149 offset:20480
	ds_read_b128 v[202:205], v149 offset:21504
	ds_read_b128 v[206:209], v149 offset:22528
	ds_read_b128 v[210:213], v149 offset:23552
	s_waitcnt vmcnt(8)
	s_waitcnt lgkmcnt(0)
	s_barrier
	s_waitcnt lgkmcnt(0)
	v_mfma_f32_16x16x32_bf16 v[60:63], v[150:153], v[182:185], v[60:63]
	v_mfma_f32_16x16x32_bf16 v[56:59], v[158:161], v[182:185], v[56:59]
	v_mfma_f32_16x16x32_bf16 v[44:47], v[150:153], v[190:193], v[44:47]
	v_mfma_f32_16x16x32_bf16 v[40:43], v[158:161], v[190:193], v[40:43]
	v_mfma_f32_16x16x32_bf16 v[28:31], v[150:153], v[198:201], v[28:31]
	v_mfma_f32_16x16x32_bf16 v[24:27], v[158:161], v[198:201], v[24:27]
	v_mfma_f32_16x16x32_bf16 v[12:15], v[150:153], v[206:209], v[12:15]
	v_mfma_f32_16x16x32_bf16 v[8:11], v[158:161], v[206:209], v[8:11]
	v_mfma_f32_16x16x32_bf16 v[60:63], v[154:157], v[186:189], v[60:63]
	v_mfma_f32_16x16x32_bf16 v[56:59], v[162:165], v[186:189], v[56:59]
	v_mfma_f32_16x16x32_bf16 v[44:47], v[154:157], v[194:197], v[44:47]
	v_mfma_f32_16x16x32_bf16 v[40:43], v[162:165], v[194:197], v[40:43]
	v_mfma_f32_16x16x32_bf16 v[28:31], v[154:157], v[202:205], v[28:31]
	v_mfma_f32_16x16x32_bf16 v[24:27], v[162:165], v[202:205], v[24:27]
	v_mfma_f32_16x16x32_bf16 v[12:15], v[154:157], v[210:213], v[12:15]
	v_mfma_f32_16x16x32_bf16 v[8:11], v[162:165], v[210:213], v[8:11]
	v_mfma_f32_16x16x32_bf16 v[52:55], v[166:169], v[182:185], v[52:55]
	v_mfma_f32_16x16x32_bf16 v[48:51], v[174:177], v[182:185], v[48:51]
	v_mfma_f32_16x16x32_bf16 v[36:39], v[166:169], v[190:193], v[36:39]
	v_mfma_f32_16x16x32_bf16 v[32:35], v[174:177], v[190:193], v[32:35]
	v_mfma_f32_16x16x32_bf16 v[20:23], v[166:169], v[198:201], v[20:23]
	v_mfma_f32_16x16x32_bf16 v[16:19], v[174:177], v[198:201], v[16:19]
	v_mfma_f32_16x16x32_bf16 v[4:7], v[166:169], v[206:209], v[4:7]
	v_mfma_f32_16x16x32_bf16 v[0:3], v[174:177], v[206:209], v[0:3]
	v_mfma_f32_16x16x32_bf16 v[52:55], v[170:173], v[186:189], v[52:55]
	v_mfma_f32_16x16x32_bf16 v[48:51], v[178:181], v[186:189], v[48:51]
	v_mfma_f32_16x16x32_bf16 v[36:39], v[170:173], v[194:197], v[36:39]
	v_mfma_f32_16x16x32_bf16 v[32:35], v[178:181], v[194:197], v[32:35]
	v_mfma_f32_16x16x32_bf16 v[20:23], v[170:173], v[202:205], v[20:23]
	v_mfma_f32_16x16x32_bf16 v[16:19], v[178:181], v[202:205], v[16:19]
	v_mfma_f32_16x16x32_bf16 v[4:7], v[170:173], v[210:213], v[4:7]
	v_mfma_f32_16x16x32_bf16 v[0:3], v[178:181], v[210:213], v[0:3]
	s_barrier
	s_add_i32 s60, 0, 0x18000
	s_add_i32 s61, 0, 0x1c000
	v_add_u32_e32 v162, s60, v144
	v_add_u32_e32 v178, s61, v144
	ds_read_b128 v[150:153], v162
	ds_read_b128 v[154:157], v162 offset:1024
	ds_read_b128 v[158:161], v162 offset:2048
	ds_read_b128 v[162:165], v162 offset:3072
	ds_read_b128 v[166:169], v178
	ds_read_b128 v[170:173], v178 offset:1024
	ds_read_b128 v[174:177], v178 offset:2048
	ds_read_b128 v[178:181], v178 offset:3072
	s_add_u32 s36, s42, 0x80000
	s_addc_u32 s37, s43, 0
	s_mov_b32 m0, s45
	v_lshl_add_u64 v[182:183], s[36:37], 0, v[128:129]
	global_load_lds_dwordx4 v[182:183], off
	v_lshl_add_u64 v[182:183], s[36:37], 0, v[132:133]
	s_mov_b32 m0, s46
	s_nop 0
	global_load_lds_dwordx4 v[182:183], off
	ds_read_b128 v[182:185], v149 offset:32768
	ds_read_b128 v[186:189], v149 offset:33792
	ds_read_b128 v[190:193], v149 offset:34816
	ds_read_b128 v[194:197], v149 offset:35840
	ds_read_b128 v[198:201], v149 offset:36864
	ds_read_b128 v[202:205], v149 offset:37888
	ds_read_b128 v[206:209], v149 offset:38912
	ds_read_b128 v[210:213], v149 offset:39936
	s_waitcnt vmcnt(8)
	s_waitcnt lgkmcnt(0)
	s_barrier
	s_waitcnt lgkmcnt(0)
	v_mfma_f32_16x16x32_bf16 v[124:127], v[150:153], v[182:185], v[124:127]
	v_mfma_f32_16x16x32_bf16 v[120:123], v[158:161], v[182:185], v[120:123]
	v_mfma_f32_16x16x32_bf16 v[108:111], v[150:153], v[190:193], v[108:111]
	v_mfma_f32_16x16x32_bf16 v[104:107], v[158:161], v[190:193], v[104:107]
	v_mfma_f32_16x16x32_bf16 v[92:95], v[150:153], v[198:201], v[92:95]
	v_mfma_f32_16x16x32_bf16 v[88:91], v[158:161], v[198:201], v[88:91]
	v_mfma_f32_16x16x32_bf16 v[76:79], v[150:153], v[206:209], v[76:79]
	v_mfma_f32_16x16x32_bf16 v[72:75], v[158:161], v[206:209], v[72:75]
	v_mfma_f32_16x16x32_bf16 v[124:127], v[154:157], v[186:189], v[124:127]
	v_mfma_f32_16x16x32_bf16 v[120:123], v[162:165], v[186:189], v[120:123]
	v_mfma_f32_16x16x32_bf16 v[108:111], v[154:157], v[194:197], v[108:111]
	v_mfma_f32_16x16x32_bf16 v[104:107], v[162:165], v[194:197], v[104:107]
	v_mfma_f32_16x16x32_bf16 v[92:95], v[154:157], v[202:205], v[92:95]
	v_mfma_f32_16x16x32_bf16 v[88:91], v[162:165], v[202:205], v[88:91]
	v_mfma_f32_16x16x32_bf16 v[76:79], v[154:157], v[210:213], v[76:79]
	v_mfma_f32_16x16x32_bf16 v[72:75], v[162:165], v[210:213], v[72:75]
	v_mfma_f32_16x16x32_bf16 v[116:119], v[166:169], v[182:185], v[116:119]
	v_mfma_f32_16x16x32_bf16 v[112:115], v[174:177], v[182:185], v[112:115]
	v_mfma_f32_16x16x32_bf16 v[100:103], v[166:169], v[190:193], v[100:103]
	v_mfma_f32_16x16x32_bf16 v[96:99], v[174:177], v[190:193], v[96:99]
	v_mfma_f32_16x16x32_bf16 v[84:87], v[166:169], v[198:201], v[84:87]
	v_mfma_f32_16x16x32_bf16 v[80:83], v[174:177], v[198:201], v[80:83]
	v_mfma_f32_16x16x32_bf16 v[68:71], v[166:169], v[206:209], v[68:71]
	v_mfma_f32_16x16x32_bf16 v[64:67], v[174:177], v[206:209], v[64:67]
	v_mfma_f32_16x16x32_bf16 v[116:119], v[170:173], v[186:189], v[116:119]
	v_mfma_f32_16x16x32_bf16 v[112:115], v[178:181], v[186:189], v[112:115]
	v_mfma_f32_16x16x32_bf16 v[100:103], v[170:173], v[194:197], v[100:103]
	v_mfma_f32_16x16x32_bf16 v[96:99], v[178:181], v[194:197], v[96:99]
	v_mfma_f32_16x16x32_bf16 v[84:87], v[170:173], v[202:205], v[84:87]
	v_mfma_f32_16x16x32_bf16 v[80:83], v[178:181], v[202:205], v[80:83]
	v_mfma_f32_16x16x32_bf16 v[68:71], v[170:173], v[210:213], v[68:71]
	v_mfma_f32_16x16x32_bf16 v[64:67], v[178:181], v[210:213], v[64:67]
	s_barrier
	s_add_i32 s36, s60, s11
	v_lshl_add_u64 v[182:183], v[214:215], 0, s[14:15]
	s_mov_b32 m0, s36
	s_nop 0
	global_load_lds_dwordx4 v[182:183], off
	s_add_i32 m0, s36, 0x2000
	s_add_u32 s36, s40, 0x80080
	v_lshl_add_u64 v[182:183], v[216:217], 0, s[14:15]
	s_addc_u32 s37, s41, 0
	s_add_i32 s40, s61, s11
	global_load_lds_dwordx4 v[182:183], off
	v_lshl_add_u64 v[182:183], s[36:37], 0, v[130:131]
	s_mov_b32 m0, s40
	s_nop 0
	global_load_lds_dwordx4 v[182:183], off
	v_lshl_add_u64 v[182:183], s[36:37], 0, v[134:135]
	s_add_i32 m0, s40, 0x2000
	s_nop 0
	global_load_lds_dwordx4 v[182:183], off
	v_lshl_add_u64 v[182:183], v[218:219], 0, s[14:15]
	s_mov_b32 m0, s49
	s_nop 0
	global_load_lds_dwordx4 v[182:183], off
	v_lshl_add_u64 v[182:183], v[220:221], 0, s[14:15]
	s_mov_b32 m0, s50
	s_nop 0
	global_load_lds_dwordx4 v[182:183], off
	ds_read_b128 v[182:185], v149 offset:49152
	ds_read_b128 v[186:189], v149 offset:50176
	ds_read_b128 v[190:193], v149 offset:51200
	ds_read_b128 v[194:197], v149 offset:52224
	ds_read_b128 v[198:201], v149 offset:53248
	ds_read_b128 v[202:205], v149 offset:54272
	ds_read_b128 v[206:209], v149 offset:55296
	ds_read_b128 v[210:213], v149 offset:56320
	s_waitcnt vmcnt(8)
	s_waitcnt lgkmcnt(0)
	s_barrier
	s_waitcnt lgkmcnt(0)
	v_mfma_f32_16x16x32_bf16 v[60:63], v[150:153], v[182:185], v[60:63]
	v_mfma_f32_16x16x32_bf16 v[56:59], v[158:161], v[182:185], v[56:59]
	v_mfma_f32_16x16x32_bf16 v[44:47], v[150:153], v[190:193], v[44:47]
	v_mfma_f32_16x16x32_bf16 v[40:43], v[158:161], v[190:193], v[40:43]
	v_mfma_f32_16x16x32_bf16 v[28:31], v[150:153], v[198:201], v[28:31]
	v_mfma_f32_16x16x32_bf16 v[24:27], v[158:161], v[198:201], v[24:27]
	v_mfma_f32_16x16x32_bf16 v[12:15], v[150:153], v[206:209], v[12:15]
	v_mfma_f32_16x16x32_bf16 v[8:11], v[158:161], v[206:209], v[8:11]
	v_mfma_f32_16x16x32_bf16 v[60:63], v[154:157], v[186:189], v[60:63]
	v_mfma_f32_16x16x32_bf16 v[56:59], v[162:165], v[186:189], v[56:59]
	v_mfma_f32_16x16x32_bf16 v[44:47], v[154:157], v[194:197], v[44:47]
	v_mfma_f32_16x16x32_bf16 v[40:43], v[162:165], v[194:197], v[40:43]
	v_mfma_f32_16x16x32_bf16 v[28:31], v[154:157], v[202:205], v[28:31]
	v_mfma_f32_16x16x32_bf16 v[24:27], v[162:165], v[202:205], v[24:27]
	v_mfma_f32_16x16x32_bf16 v[12:15], v[154:157], v[210:213], v[12:15]
	v_mfma_f32_16x16x32_bf16 v[8:11], v[162:165], v[210:213], v[8:11]
	v_mfma_f32_16x16x32_bf16 v[52:55], v[166:169], v[182:185], v[52:55]
	v_mfma_f32_16x16x32_bf16 v[48:51], v[174:177], v[182:185], v[48:51]
	v_mfma_f32_16x16x32_bf16 v[36:39], v[166:169], v[190:193], v[36:39]
	v_mfma_f32_16x16x32_bf16 v[32:35], v[174:177], v[190:193], v[32:35]
	v_mfma_f32_16x16x32_bf16 v[20:23], v[166:169], v[198:201], v[20:23]
	v_mfma_f32_16x16x32_bf16 v[16:19], v[174:177], v[198:201], v[16:19]
	v_mfma_f32_16x16x32_bf16 v[4:7], v[166:169], v[206:209], v[4:7]
	v_mfma_f32_16x16x32_bf16 v[0:3], v[174:177], v[206:209], v[0:3]
	v_mfma_f32_16x16x32_bf16 v[52:55], v[170:173], v[186:189], v[52:55]
	v_mfma_f32_16x16x32_bf16 v[48:51], v[178:181], v[186:189], v[48:51]
	v_mfma_f32_16x16x32_bf16 v[36:39], v[170:173], v[194:197], v[36:39]
	v_mfma_f32_16x16x32_bf16 v[32:35], v[178:181], v[194:197], v[32:35]
	v_mfma_f32_16x16x32_bf16 v[20:23], v[170:173], v[202:205], v[20:23]
	v_mfma_f32_16x16x32_bf16 v[16:19], v[178:181], v[202:205], v[16:19]
	v_mfma_f32_16x16x32_bf16 v[4:7], v[170:173], v[210:213], v[4:7]
	v_mfma_f32_16x16x32_bf16 v[0:3], v[178:181], v[210:213], v[0:3]
	s_barrier
	s_add_i32 s59, s59, 2
	s_add_u32 s57, s57, 0x100
	s_addc_u32 s58, s58, 0
	s_cmp_gt_u32 s59, 29
	s_mov_b64 s[36:37], s[38:39]
	s_cbranch_scc0 .LBB0_159
	s_and_b64 vcc, exec, s[6:7]
	s_cbranch_vccz .LBB0_162
	s_barrier

.Lgprio1:
.LBB0_248:
	ds_read_b128 v[144:147], v161
	ds_read_b128 v[148:151], v161 offset:1024
	ds_read_b128 v[152:155], v161 offset:2048
	ds_read_b128 v[164:167], v161 offset:3072
	ds_read_b128 v[168:171], v162
	ds_read_b128 v[172:175], v162 offset:1024
	ds_read_b128 v[176:179], v162 offset:2048
	ds_read_b128 v[180:183], v162 offset:3072
	s_add_u32 s6, s8, 0x100
	s_addc_u32 s7, s9, 0
	s_cmpk_eq_i32 s65, 0x54
	s_cselect_b32 s49, s43, s7
	s_cselect_b32 s48, s42, s6
	s_cselect_b32 s47, s45, s64
	s_cselect_b32 s46, s44, s63
	v_lshl_add_u64 v[184:185], s[8:9], 0, v[136:137]
	s_add_i32 m0, s53, 0xc000
	s_nop 0
	global_load_lds_dwordx4 v[184:185], off
	v_lshl_add_u64 v[184:185], s[8:9], 0, v[138:139]
	s_add_i32 m0, s53, 0xe000
	s_nop 0
	global_load_lds_dwordx4 v[184:185], off
	ds_read_b128 v[184:187], v163
	ds_read_b128 v[188:191], v163 offset:1024
	ds_read_b128 v[192:195], v163 offset:2048
	ds_read_b128 v[196:199], v163 offset:3072
	ds_read_b128 v[200:203], v163 offset:4096
	ds_read_b128 v[204:207], v163 offset:5120
	ds_read_b128 v[208:211], v163 offset:6144
	ds_read_b128 v[212:215], v163 offset:7168
	s_waitcnt vmcnt(8)
	s_waitcnt lgkmcnt(0)
	s_barrier
	s_waitcnt lgkmcnt(0)
	v_mfma_f32_16x16x32_bf16 v[124:127], v[144:147], v[184:187], v[124:127]
	v_mfma_f32_16x16x32_bf16 v[120:123], v[152:155], v[184:187], v[120:123]
	v_mfma_f32_16x16x32_bf16 v[108:111], v[144:147], v[192:195], v[108:111]
	v_mfma_f32_16x16x32_bf16 v[104:107], v[152:155], v[192:195], v[104:107]
	v_mfma_f32_16x16x32_bf16 v[92:95], v[144:147], v[200:203], v[92:95]
	v_mfma_f32_16x16x32_bf16 v[88:91], v[152:155], v[200:203], v[88:91]
	v_mfma_f32_16x16x32_bf16 v[76:79], v[144:147], v[208:211], v[76:79]
	v_mfma_f32_16x16x32_bf16 v[72:75], v[152:155], v[208:211], v[72:75]
	v_mfma_f32_16x16x32_bf16 v[124:127], v[148:151], v[188:191], v[124:127]
	v_mfma_f32_16x16x32_bf16 v[120:123], v[164:167], v[188:191], v[120:123]
	v_mfma_f32_16x16x32_bf16 v[108:111], v[148:151], v[196:199], v[108:111]
	v_mfma_f32_16x16x32_bf16 v[104:107], v[164:167], v[196:199], v[104:107]
	v_mfma_f32_16x16x32_bf16 v[92:95], v[148:151], v[204:207], v[92:95]
	v_mfma_f32_16x16x32_bf16 v[88:91], v[164:167], v[204:207], v[88:91]
	v_mfma_f32_16x16x32_bf16 v[76:79], v[148:151], v[212:215], v[76:79]
	v_mfma_f32_16x16x32_bf16 v[72:75], v[164:167], v[212:215], v[72:75]
	v_mfma_f32_16x16x32_bf16 v[116:119], v[168:171], v[184:187], v[116:119]
	v_mfma_f32_16x16x32_bf16 v[112:115], v[176:179], v[184:187], v[112:115]
	v_mfma_f32_16x16x32_bf16 v[100:103], v[168:171], v[192:195], v[100:103]
	v_mfma_f32_16x16x32_bf16 v[96:99], v[176:179], v[192:195], v[96:99]
	v_mfma_f32_16x16x32_bf16 v[84:87], v[168:171], v[200:203], v[84:87]
	v_mfma_f32_16x16x32_bf16 v[80:83], v[176:179], v[200:203], v[80:83]
	v_mfma_f32_16x16x32_bf16 v[68:71], v[168:171], v[208:211], v[68:71]
	v_mfma_f32_16x16x32_bf16 v[64:67], v[176:179], v[208:211], v[64:67]
	v_mfma_f32_16x16x32_bf16 v[116:119], v[172:175], v[188:191], v[116:119]
	v_mfma_f32_16x16x32_bf16 v[112:115], v[180:183], v[188:191], v[112:115]
	v_mfma_f32_16x16x32_bf16 v[100:103], v[172:175], v[196:199], v[100:103]
	v_mfma_f32_16x16x32_bf16 v[96:99], v[180:183], v[196:199], v[96:99]
	v_mfma_f32_16x16x32_bf16 v[84:87], v[172:175], v[204:207], v[84:87]
	v_mfma_f32_16x16x32_bf16 v[80:83], v[180:183], v[204:207], v[80:83]
	v_mfma_f32_16x16x32_bf16 v[68:71], v[172:175], v[212:215], v[68:71]
	v_mfma_f32_16x16x32_bf16 v[64:67], v[180:183], v[212:215], v[64:67]
	s_barrier
	s_add_i32 s8, s58, s21
	v_lshl_add_u64 v[216:217], s[46:47], 0, v[130:131]
	s_mov_b32 m0, s8
	v_lshl_add_u64 v[218:219], s[46:47], 0, v[134:135]
	global_load_lds_dwordx4 v[216:217], off
	s_add_i32 m0, s8, 0x2000
	s_add_u32 s8, s46, 0x160000
	s_addc_u32 s9, s47, 0
	s_add_i32 s66, s59, s21
	global_load_lds_dwordx4 v[218:219], off
	v_lshl_add_u64 v[184:185], s[8:9], 0, v[130:131]
	s_mov_b32 m0, s66
	v_lshl_add_u64 v[220:221], s[48:49], 0, v[128:129]
	global_load_lds_dwordx4 v[184:185], off
	v_lshl_add_u64 v[184:185], s[8:9], 0, v[134:135]
	s_add_i32 m0, s66, 0x2000
	v_lshl_add_u64 v[222:223], s[48:49], 0, v[132:133]
	global_load_lds_dwordx4 v[184:185], off
	s_mov_b32 m0, s53
	s_nop 0
	global_load_lds_dwordx4 v[220:221], off
	s_mov_b32 m0, s54
	s_nop 0
	global_load_lds_dwordx4 v[222:223], off
	ds_read_b128 v[184:187], v163 offset:16384
	ds_read_b128 v[188:191], v163 offset:17408
	ds_read_b128 v[192:195], v163 offset:18432
	ds_read_b128 v[196:199], v163 offset:19456
	ds_read_b128 v[200:203], v163 offset:20480
	ds_read_b128 v[204:207], v163 offset:21504
	ds_read_b128 v[208:211], v163 offset:22528
	ds_read_b128 v[212:215], v163 offset:23552
	s_waitcnt vmcnt(8)
	s_waitcnt lgkmcnt(0)
	s_barrier
	s_waitcnt lgkmcnt(0)
	v_mfma_f32_16x16x32_bf16 v[60:63], v[144:147], v[184:187], v[60:63]
	v_mfma_f32_16x16x32_bf16 v[56:59], v[152:155], v[184:187], v[56:59]
	v_mfma_f32_16x16x32_bf16 v[44:47], v[144:147], v[192:195], v[44:47]
	v_mfma_f32_16x16x32_bf16 v[40:43], v[152:155], v[192:195], v[40:43]
	v_mfma_f32_16x16x32_bf16 v[28:31], v[144:147], v[200:203], v[28:31]
	v_mfma_f32_16x16x32_bf16 v[24:27], v[152:155], v[200:203], v[24:27]
	v_mfma_f32_16x16x32_bf16 v[12:15], v[144:147], v[208:211], v[12:15]
	v_mfma_f32_16x16x32_bf16 v[8:11], v[152:155], v[208:211], v[8:11]
	v_mfma_f32_16x16x32_bf16 v[60:63], v[148:151], v[188:191], v[60:63]
	v_mfma_f32_16x16x32_bf16 v[56:59], v[164:167], v[188:191], v[56:59]
	v_mfma_f32_16x16x32_bf16 v[44:47], v[148:151], v[196:199], v[44:47]
	v_mfma_f32_16x16x32_bf16 v[40:43], v[164:167], v[196:199], v[40:43]
	v_mfma_f32_16x16x32_bf16 v[28:31], v[148:151], v[204:207], v[28:31]
	v_mfma_f32_16x16x32_bf16 v[24:27], v[164:167], v[204:207], v[24:27]
	v_mfma_f32_16x16x32_bf16 v[12:15], v[148:151], v[212:215], v[12:15]
	v_mfma_f32_16x16x32_bf16 v[8:11], v[164:167], v[212:215], v[8:11]
	v_mfma_f32_16x16x32_bf16 v[52:55], v[168:171], v[184:187], v[52:55]
	v_mfma_f32_16x16x32_bf16 v[48:51], v[176:179], v[184:187], v[48:51]
	v_mfma_f32_16x16x32_bf16 v[36:39], v[168:171], v[192:195], v[36:39]
	v_mfma_f32_16x16x32_bf16 v[32:35], v[176:179], v[192:195], v[32:35]
	v_mfma_f32_16x16x32_bf16 v[20:23], v[168:171], v[200:203], v[20:23]
	v_mfma_f32_16x16x32_bf16 v[16:19], v[176:179], v[200:203], v[16:19]
	v_mfma_f32_16x16x32_bf16 v[4:7], v[168:171], v[208:211], v[4:7]
	v_mfma_f32_16x16x32_bf16 v[0:3], v[176:179], v[208:211], v[0:3]
	v_mfma_f32_16x16x32_bf16 v[52:55], v[172:175], v[188:191], v[52:55]
	v_mfma_f32_16x16x32_bf16 v[48:51], v[180:183], v[188:191], v[48:51]
	v_mfma_f32_16x16x32_bf16 v[36:39], v[172:175], v[196:199], v[36:39]
	v_mfma_f32_16x16x32_bf16 v[32:35], v[180:183], v[196:199], v[32:35]
	v_mfma_f32_16x16x32_bf16 v[20:23], v[172:175], v[204:207], v[20:23]
	v_mfma_f32_16x16x32_bf16 v[16:19], v[180:183], v[204:207], v[16:19]
	v_mfma_f32_16x16x32_bf16 v[4:7], v[172:175], v[212:215], v[4:7]
	v_mfma_f32_16x16x32_bf16 v[0:3], v[180:183], v[212:215], v[0:3]
	s_barrier
	s_add_i32 s66, 0, 0x18000
	s_add_i32 s67, 0, 0x1c000
	v_add_u32_e32 v164, s66, v156
	v_add_u32_e32 v180, s67, v156
	ds_read_b128 v[144:147], v164
	ds_read_b128 v[148:151], v164 offset:1024
	ds_read_b128 v[152:155], v164 offset:2048
	ds_read_b128 v[164:167], v164 offset:3072
	ds_read_b128 v[168:171], v180
	ds_read_b128 v[172:175], v180 offset:1024
	ds_read_b128 v[176:179], v180 offset:2048
	ds_read_b128 v[180:183], v180 offset:3072
	s_add_u32 s8, s48, 0x160000
	s_addc_u32 s9, s49, 0
	s_mov_b32 m0, s55
	v_lshl_add_u64 v[184:185], s[8:9], 0, v[128:129]
	global_load_lds_dwordx4 v[184:185], off
	v_lshl_add_u64 v[184:185], s[8:9], 0, v[132:133]
	s_mov_b32 m0, s56
	s_nop 0
	global_load_lds_dwordx4 v[184:185], off
	ds_read_b128 v[184:187], v163 offset:32768
	ds_read_b128 v[188:191], v163 offset:33792
	ds_read_b128 v[192:195], v163 offset:34816
	ds_read_b128 v[196:199], v163 offset:35840
	ds_read_b128 v[200:203], v163 offset:36864
	ds_read_b128 v[204:207], v163 offset:37888
	ds_read_b128 v[208:211], v163 offset:38912
	ds_read_b128 v[212:215], v163 offset:39936
	s_waitcnt vmcnt(8)
	s_waitcnt lgkmcnt(0)
	s_barrier
	s_waitcnt lgkmcnt(0)
	v_mfma_f32_16x16x32_bf16 v[124:127], v[144:147], v[184:187], v[124:127]
	v_mfma_f32_16x16x32_bf16 v[120:123], v[152:155], v[184:187], v[120:123]
	v_mfma_f32_16x16x32_bf16 v[108:111], v[144:147], v[192:195], v[108:111]
	v_mfma_f32_16x16x32_bf16 v[104:107], v[152:155], v[192:195], v[104:107]
	v_mfma_f32_16x16x32_bf16 v[92:95], v[144:147], v[200:203], v[92:95]
	v_mfma_f32_16x16x32_bf16 v[88:91], v[152:155], v[200:203], v[88:91]
	v_mfma_f32_16x16x32_bf16 v[76:79], v[144:147], v[208:211], v[76:79]
	v_mfma_f32_16x16x32_bf16 v[72:75], v[152:155], v[208:211], v[72:75]
	v_mfma_f32_16x16x32_bf16 v[124:127], v[148:151], v[188:191], v[124:127]
	v_mfma_f32_16x16x32_bf16 v[120:123], v[164:167], v[188:191], v[120:123]
	v_mfma_f32_16x16x32_bf16 v[108:111], v[148:151], v[196:199], v[108:111]
	v_mfma_f32_16x16x32_bf16 v[104:107], v[164:167], v[196:199], v[104:107]
	v_mfma_f32_16x16x32_bf16 v[92:95], v[148:151], v[204:207], v[92:95]
	v_mfma_f32_16x16x32_bf16 v[88:91], v[164:167], v[204:207], v[88:91]
	v_mfma_f32_16x16x32_bf16 v[76:79], v[148:151], v[212:215], v[76:79]
	v_mfma_f32_16x16x32_bf16 v[72:75], v[164:167], v[212:215], v[72:75]
	v_mfma_f32_16x16x32_bf16 v[116:119], v[168:171], v[184:187], v[116:119]
	v_mfma_f32_16x16x32_bf16 v[112:115], v[176:179], v[184:187], v[112:115]
	v_mfma_f32_16x16x32_bf16 v[100:103], v[168:171], v[192:195], v[100:103]
	v_mfma_f32_16x16x32_bf16 v[96:99], v[176:179], v[192:195], v[96:99]
	v_mfma_f32_16x16x32_bf16 v[84:87], v[168:171], v[200:203], v[84:87]
	v_mfma_f32_16x16x32_bf16 v[80:83], v[176:179], v[200:203], v[80:83]
	v_mfma_f32_16x16x32_bf16 v[68:71], v[168:171], v[208:211], v[68:71]
	v_mfma_f32_16x16x32_bf16 v[64:67], v[176:179], v[208:211], v[64:67]
	v_mfma_f32_16x16x32_bf16 v[116:119], v[172:175], v[188:191], v[116:119]
	v_mfma_f32_16x16x32_bf16 v[112:115], v[180:183], v[188:191], v[112:115]
	v_mfma_f32_16x16x32_bf16 v[100:103], v[172:175], v[196:199], v[100:103]
	v_mfma_f32_16x16x32_bf16 v[96:99], v[180:183], v[196:199], v[96:99]
	v_mfma_f32_16x16x32_bf16 v[84:87], v[172:175], v[204:207], v[84:87]
	v_mfma_f32_16x16x32_bf16 v[80:83], v[180:183], v[204:207], v[80:83]
	v_mfma_f32_16x16x32_bf16 v[68:71], v[172:175], v[212:215], v[68:71]
	v_mfma_f32_16x16x32_bf16 v[64:67], v[180:183], v[212:215], v[64:67]
	s_barrier
	s_add_i32 s8, s66, s21
	v_lshl_add_u64 v[184:185], v[216:217], 0, s[36:37]
	s_mov_b32 m0, s8
	s_nop 0
	global_load_lds_dwordx4 v[184:185], off
	s_add_i32 m0, s8, 0x2000
	s_add_u32 s8, s46, 0x160080
	v_lshl_add_u64 v[184:185], v[218:219], 0, s[36:37]
	s_addc_u32 s9, s47, 0
	s_add_i32 s46, s67, s21
	global_load_lds_dwordx4 v[184:185], off
	v_lshl_add_u64 v[184:185], s[8:9], 0, v[130:131]
	s_mov_b32 m0, s46
	s_nop 0
	global_load_lds_dwordx4 v[184:185], off
	v_lshl_add_u64 v[184:185], s[8:9], 0, v[134:135]
	s_add_i32 m0, s46, 0x2000
	s_nop 0
	global_load_lds_dwordx4 v[184:185], off
	v_lshl_add_u64 v[184:185], v[220:221], 0, s[36:37]
	s_mov_b32 m0, s26
	s_nop 0
	global_load_lds_dwordx4 v[184:185], off
	v_lshl_add_u64 v[184:185], v[222:223], 0, s[36:37]
	s_mov_b32 m0, s27
	s_nop 0
	global_load_lds_dwordx4 v[184:185], off
	ds_read_b128 v[184:187], v163 offset:49152
	ds_read_b128 v[188:191], v163 offset:50176
	ds_read_b128 v[192:195], v163 offset:51200
	ds_read_b128 v[196:199], v163 offset:52224
	ds_read_b128 v[200:203], v163 offset:53248
	ds_read_b128 v[204:207], v163 offset:54272
	ds_read_b128 v[208:211], v163 offset:55296
	ds_read_b128 v[212:215], v163 offset:56320
	s_waitcnt vmcnt(8)
	s_waitcnt lgkmcnt(0)
	s_barrier
	s_waitcnt lgkmcnt(0)
	v_mfma_f32_16x16x32_bf16 v[60:63], v[144:147], v[184:187], v[60:63]
	v_mfma_f32_16x16x32_bf16 v[56:59], v[152:155], v[184:187], v[56:59]
	v_mfma_f32_16x16x32_bf16 v[44:47], v[144:147], v[192:195], v[44:47]
	v_mfma_f32_16x16x32_bf16 v[40:43], v[152:155], v[192:195], v[40:43]
	v_mfma_f32_16x16x32_bf16 v[28:31], v[144:147], v[200:203], v[28:31]
	v_mfma_f32_16x16x32_bf16 v[24:27], v[152:155], v[200:203], v[24:27]
	v_mfma_f32_16x16x32_bf16 v[12:15], v[144:147], v[208:211], v[12:15]
	v_mfma_f32_16x16x32_bf16 v[8:11], v[152:155], v[208:211], v[8:11]
	v_mfma_f32_16x16x32_bf16 v[60:63], v[148:151], v[188:191], v[60:63]
	v_mfma_f32_16x16x32_bf16 v[56:59], v[164:167], v[188:191], v[56:59]
	v_mfma_f32_16x16x32_bf16 v[44:47], v[148:151], v[196:199], v[44:47]
	v_mfma_f32_16x16x32_bf16 v[40:43], v[164:167], v[196:199], v[40:43]
	v_mfma_f32_16x16x32_bf16 v[28:31], v[148:151], v[204:207], v[28:31]
	v_mfma_f32_16x16x32_bf16 v[24:27], v[164:167], v[204:207], v[24:27]
	v_mfma_f32_16x16x32_bf16 v[12:15], v[148:151], v[212:215], v[12:15]
	v_mfma_f32_16x16x32_bf16 v[8:11], v[164:167], v[212:215], v[8:11]
	v_mfma_f32_16x16x32_bf16 v[52:55], v[168:171], v[184:187], v[52:55]
	v_mfma_f32_16x16x32_bf16 v[48:51], v[176:179], v[184:187], v[48:51]
	v_mfma_f32_16x16x32_bf16 v[36:39], v[168:171], v[192:195], v[36:39]
	v_mfma_f32_16x16x32_bf16 v[32:35], v[176:179], v[192:195], v[32:35]
	v_mfma_f32_16x16x32_bf16 v[20:23], v[168:171], v[200:203], v[20:23]
	v_mfma_f32_16x16x32_bf16 v[16:19], v[176:179], v[200:203], v[16:19]
	v_mfma_f32_16x16x32_bf16 v[4:7], v[168:171], v[208:211], v[4:7]
	v_mfma_f32_16x16x32_bf16 v[0:3], v[176:179], v[208:211], v[0:3]
	v_mfma_f32_16x16x32_bf16 v[52:55], v[172:175], v[188:191], v[52:55]
	v_mfma_f32_16x16x32_bf16 v[48:51], v[180:183], v[188:191], v[48:51]
	v_mfma_f32_16x16x32_bf16 v[36:39], v[172:175], v[196:199], v[36:39]
	v_mfma_f32_16x16x32_bf16 v[32:35], v[180:183], v[196:199], v[32:35]
	v_mfma_f32_16x16x32_bf16 v[20:23], v[172:175], v[204:207], v[20:23]
	v_mfma_f32_16x16x32_bf16 v[16:19], v[180:183], v[204:207], v[16:19]
	v_mfma_f32_16x16x32_bf16 v[4:7], v[172:175], v[212:215], v[4:7]
	v_mfma_f32_16x16x32_bf16 v[0:3], v[180:183], v[212:215], v[0:3]
	s_barrier
	s_add_i32 s65, s65, 2
	s_add_u32 s63, s63, 0x100
	s_addc_u32 s64, s64, 0
	s_cmpk_gt_u32 s65, 0x55
	s_mov_b64 s[8:9], s[6:7]
	s_cbranch_scc0 .LBB0_248
	s_and_b64 vcc, exec, s[28:29]
	s_cbranch_vccz .LBB0_251
	s_barrier

.Lgprio2:
.LBB0_387:
	ds_read_b128 v[146:149], v156
	ds_read_b128 v[160:163], v156 offset:1024
	ds_read_b128 v[164:167], v156 offset:2048
	ds_read_b128 v[168:171], v156 offset:3072
	ds_read_b128 v[172:175], v157
	ds_read_b128 v[176:179], v157 offset:1024
	ds_read_b128 v[180:183], v157 offset:2048
	ds_read_b128 v[184:187], v157 offset:3072
	s_add_u32 s38, s36, 0x100
	s_addc_u32 s39, s37, 0
	s_cmp_eq_u32 s64, 28
	s_cselect_b32 s43, s29, s39
	s_cselect_b32 s42, s60, s38
	s_cselect_b32 s41, s19, s63
	s_cselect_b32 s40, s61, s62
	v_lshl_add_u64 v[150:151], s[36:37], 0, v[138:139]
	s_add_i32 m0, s46, 0xc000
	s_nop 0
	global_load_lds_dwordx4 v[150:151], off
	v_lshl_add_u64 v[150:151], s[36:37], 0, v[140:141]
	s_add_i32 m0, s46, 0xe000
	s_nop 0
	global_load_lds_dwordx4 v[150:151], off
	ds_read_b128 v[188:191], v158
	ds_read_b128 v[192:195], v158 offset:1024
	ds_read_b128 v[196:199], v158 offset:2048
	ds_read_b128 v[200:203], v158 offset:3072
	ds_read_b128 v[204:207], v158 offset:4096
	ds_read_b128 v[208:211], v158 offset:5120
	ds_read_b128 v[212:215], v158 offset:6144
	ds_read_b128 v[216:219], v158 offset:7168
	s_waitcnt vmcnt(8)
	s_waitcnt lgkmcnt(0)
	s_barrier
	s_waitcnt lgkmcnt(0)
	v_mfma_f32_16x16x32_bf16 v[124:127], v[146:149], v[188:191], v[124:127]
	v_mfma_f32_16x16x32_bf16 v[120:123], v[164:167], v[188:191], v[120:123]
	v_mfma_f32_16x16x32_bf16 v[108:111], v[146:149], v[196:199], v[108:111]
	v_mfma_f32_16x16x32_bf16 v[104:107], v[164:167], v[196:199], v[104:107]
	v_mfma_f32_16x16x32_bf16 v[92:95], v[146:149], v[204:207], v[92:95]
	v_mfma_f32_16x16x32_bf16 v[88:91], v[164:167], v[204:207], v[88:91]
	v_mfma_f32_16x16x32_bf16 v[76:79], v[146:149], v[212:215], v[76:79]
	v_mfma_f32_16x16x32_bf16 v[72:75], v[164:167], v[212:215], v[72:75]
	v_mfma_f32_16x16x32_bf16 v[124:127], v[160:163], v[192:195], v[124:127]
	v_mfma_f32_16x16x32_bf16 v[120:123], v[168:171], v[192:195], v[120:123]
	v_mfma_f32_16x16x32_bf16 v[108:111], v[160:163], v[200:203], v[108:111]
	v_mfma_f32_16x16x32_bf16 v[104:107], v[168:171], v[200:203], v[104:107]
	v_mfma_f32_16x16x32_bf16 v[92:95], v[160:163], v[208:211], v[92:95]
	v_mfma_f32_16x16x32_bf16 v[88:91], v[168:171], v[208:211], v[88:91]
	v_mfma_f32_16x16x32_bf16 v[76:79], v[160:163], v[216:219], v[76:79]
	v_mfma_f32_16x16x32_bf16 v[72:75], v[168:171], v[216:219], v[72:75]
	v_mfma_f32_16x16x32_bf16 v[116:119], v[172:175], v[188:191], v[116:119]
	v_mfma_f32_16x16x32_bf16 v[112:115], v[180:183], v[188:191], v[112:115]
	v_mfma_f32_16x16x32_bf16 v[100:103], v[172:175], v[196:199], v[100:103]
	v_mfma_f32_16x16x32_bf16 v[96:99], v[180:183], v[196:199], v[96:99]
	v_mfma_f32_16x16x32_bf16 v[84:87], v[172:175], v[204:207], v[84:87]
	v_mfma_f32_16x16x32_bf16 v[80:83], v[180:183], v[204:207], v[80:83]
	v_mfma_f32_16x16x32_bf16 v[68:71], v[172:175], v[212:215], v[68:71]
	v_mfma_f32_16x16x32_bf16 v[64:67], v[180:183], v[212:215], v[64:67]
	v_mfma_f32_16x16x32_bf16 v[116:119], v[176:179], v[192:195], v[116:119]
	v_mfma_f32_16x16x32_bf16 v[112:115], v[184:187], v[192:195], v[112:115]
	v_mfma_f32_16x16x32_bf16 v[100:103], v[176:179], v[200:203], v[100:103]
	v_mfma_f32_16x16x32_bf16 v[96:99], v[184:187], v[200:203], v[96:99]
	v_mfma_f32_16x16x32_bf16 v[84:87], v[176:179], v[208:211], v[84:87]
	v_mfma_f32_16x16x32_bf16 v[80:83], v[184:187], v[208:211], v[80:83]
	v_mfma_f32_16x16x32_bf16 v[68:71], v[176:179], v[216:219], v[68:71]
	v_mfma_f32_16x16x32_bf16 v[64:67], v[184:187], v[216:219], v[64:67]
	s_barrier
	s_add_i32 s36, s55, s11
	v_lshl_add_u64 v[150:151], s[40:41], 0, v[130:131]
	s_mov_b32 m0, s36
	v_lshl_add_u64 v[220:221], s[40:41], 0, v[134:135]
	global_load_lds_dwordx4 v[150:151], off
	s_add_i32 m0, s36, 0x2000
	s_add_u32 s36, s40, 0x80000
	s_addc_u32 s37, s41, 0
	s_add_i32 s65, s56, s11
	global_load_lds_dwordx4 v[220:221], off
	v_lshl_add_u64 v[188:189], s[36:37], 0, v[130:131]
	s_mov_b32 m0, s65
	v_lshl_add_u64 v[222:223], s[42:43], 0, v[128:129]
	global_load_lds_dwordx4 v[188:189], off
	v_lshl_add_u64 v[188:189], s[36:37], 0, v[134:135]
	s_add_i32 m0, s65, 0x2000
	v_lshl_add_u64 v[224:225], s[42:43], 0, v[132:133]
	global_load_lds_dwordx4 v[188:189], off
	s_mov_b32 m0, s46
	s_nop 0
	global_load_lds_dwordx4 v[222:223], off
	s_mov_b32 m0, s47
	s_nop 0
	global_load_lds_dwordx4 v[224:225], off
	ds_read_b128 v[188:191], v158 offset:16384
	ds_read_b128 v[192:195], v158 offset:17408
	ds_read_b128 v[196:199], v158 offset:18432
	ds_read_b128 v[200:203], v158 offset:19456
	ds_read_b128 v[204:207], v158 offset:20480
	ds_read_b128 v[208:211], v158 offset:21504
	ds_read_b128 v[212:215], v158 offset:22528
	ds_read_b128 v[216:219], v158 offset:23552
	s_waitcnt vmcnt(8)
	s_waitcnt lgkmcnt(0)
	s_barrier
	s_waitcnt lgkmcnt(0)
	v_mfma_f32_16x16x32_bf16 v[60:63], v[146:149], v[188:191], v[60:63]
	v_mfma_f32_16x16x32_bf16 v[56:59], v[164:167], v[188:191], v[56:59]
	v_mfma_f32_16x16x32_bf16 v[44:47], v[146:149], v[196:199], v[44:47]
	v_mfma_f32_16x16x32_bf16 v[40:43], v[164:167], v[196:199], v[40:43]
	v_mfma_f32_16x16x32_bf16 v[28:31], v[146:149], v[204:207], v[28:31]
	v_mfma_f32_16x16x32_bf16 v[24:27], v[164:167], v[204:207], v[24:27]
	v_mfma_f32_16x16x32_bf16 v[12:15], v[146:149], v[212:215], v[12:15]
	v_mfma_f32_16x16x32_bf16 v[8:11], v[164:167], v[212:215], v[8:11]
	v_mfma_f32_16x16x32_bf16 v[60:63], v[160:163], v[192:195], v[60:63]
	v_mfma_f32_16x16x32_bf16 v[56:59], v[168:171], v[192:195], v[56:59]
	v_mfma_f32_16x16x32_bf16 v[44:47], v[160:163], v[200:203], v[44:47]
	v_mfma_f32_16x16x32_bf16 v[40:43], v[168:171], v[200:203], v[40:43]
	v_mfma_f32_16x16x32_bf16 v[28:31], v[160:163], v[208:211], v[28:31]
	v_mfma_f32_16x16x32_bf16 v[24:27], v[168:171], v[208:211], v[24:27]
	v_mfma_f32_16x16x32_bf16 v[12:15], v[160:163], v[216:219], v[12:15]
	v_mfma_f32_16x16x32_bf16 v[8:11], v[168:171], v[216:219], v[8:11]
	v_mfma_f32_16x16x32_bf16 v[52:55], v[172:175], v[188:191], v[52:55]
	v_mfma_f32_16x16x32_bf16 v[48:51], v[180:183], v[188:191], v[48:51]
	v_mfma_f32_16x16x32_bf16 v[36:39], v[172:175], v[196:199], v[36:39]
	v_mfma_f32_16x16x32_bf16 v[32:35], v[180:183], v[196:199], v[32:35]
	v_mfma_f32_16x16x32_bf16 v[20:23], v[172:175], v[204:207], v[20:23]
	v_mfma_f32_16x16x32_bf16 v[16:19], v[180:183], v[204:207], v[16:19]
	v_mfma_f32_16x16x32_bf16 v[4:7], v[172:175], v[212:215], v[4:7]
	v_mfma_f32_16x16x32_bf16 v[0:3], v[180:183], v[212:215], v[0:3]
	v_mfma_f32_16x16x32_bf16 v[52:55], v[176:179], v[192:195], v[52:55]
	v_mfma_f32_16x16x32_bf16 v[48:51], v[184:187], v[192:195], v[48:51]
	v_mfma_f32_16x16x32_bf16 v[36:39], v[176:179], v[200:203], v[36:39]
	v_mfma_f32_16x16x32_bf16 v[32:35], v[184:187], v[200:203], v[32:35]
	v_mfma_f32_16x16x32_bf16 v[20:23], v[176:179], v[208:211], v[20:23]
	v_mfma_f32_16x16x32_bf16 v[16:19], v[184:187], v[208:211], v[16:19]
	v_mfma_f32_16x16x32_bf16 v[4:7], v[176:179], v[216:219], v[4:7]
	v_mfma_f32_16x16x32_bf16 v[0:3], v[184:187], v[216:219], v[0:3]
	s_barrier
	s_add_i32 s65, 0, 0x18000
	s_add_i32 s66, 0, 0x1c000
	v_add_u32_e32 v168, s65, v154
	v_add_u32_e32 v184, s66, v154
	ds_read_b128 v[146:149], v168
	ds_read_b128 v[160:163], v168 offset:1024
	ds_read_b128 v[164:167], v168 offset:2048
	ds_read_b128 v[168:171], v168 offset:3072
	ds_read_b128 v[172:175], v184
	ds_read_b128 v[176:179], v184 offset:1024
	ds_read_b128 v[180:183], v184 offset:2048
	ds_read_b128 v[184:187], v184 offset:3072
	s_add_u32 s36, s42, 0x80000
	s_addc_u32 s37, s43, 0
	s_mov_b32 m0, s48
	v_lshl_add_u64 v[188:189], s[36:37], 0, v[128:129]
	global_load_lds_dwordx4 v[188:189], off
	v_lshl_add_u64 v[188:189], s[36:37], 0, v[132:133]
	s_mov_b32 m0, s49
	s_nop 0
	global_load_lds_dwordx4 v[188:189], off
	ds_read_b128 v[188:191], v158 offset:32768
	ds_read_b128 v[192:195], v158 offset:33792
	ds_read_b128 v[196:199], v158 offset:34816
	ds_read_b128 v[200:203], v158 offset:35840
	ds_read_b128 v[204:207], v158 offset:36864
	ds_read_b128 v[208:211], v158 offset:37888
	ds_read_b128 v[212:215], v158 offset:38912
	ds_read_b128 v[216:219], v158 offset:39936
	s_waitcnt vmcnt(8)
	s_waitcnt lgkmcnt(0)
	s_barrier
	s_waitcnt lgkmcnt(0)
	v_mfma_f32_16x16x32_bf16 v[124:127], v[146:149], v[188:191], v[124:127]
	v_mfma_f32_16x16x32_bf16 v[120:123], v[164:167], v[188:191], v[120:123]
	v_mfma_f32_16x16x32_bf16 v[108:111], v[146:149], v[196:199], v[108:111]
	v_mfma_f32_16x16x32_bf16 v[104:107], v[164:167], v[196:199], v[104:107]
	v_mfma_f32_16x16x32_bf16 v[92:95], v[146:149], v[204:207], v[92:95]
	v_mfma_f32_16x16x32_bf16 v[88:91], v[164:167], v[204:207], v[88:91]
	v_mfma_f32_16x16x32_bf16 v[76:79], v[146:149], v[212:215], v[76:79]
	v_mfma_f32_16x16x32_bf16 v[72:75], v[164:167], v[212:215], v[72:75]
	v_mfma_f32_16x16x32_bf16 v[124:127], v[160:163], v[192:195], v[124:127]
	v_mfma_f32_16x16x32_bf16 v[120:123], v[168:171], v[192:195], v[120:123]
	v_mfma_f32_16x16x32_bf16 v[108:111], v[160:163], v[200:203], v[108:111]
	v_mfma_f32_16x16x32_bf16 v[104:107], v[168:171], v[200:203], v[104:107]
	v_mfma_f32_16x16x32_bf16 v[92:95], v[160:163], v[208:211], v[92:95]
	v_mfma_f32_16x16x32_bf16 v[88:91], v[168:171], v[208:211], v[88:91]
	v_mfma_f32_16x16x32_bf16 v[76:79], v[160:163], v[216:219], v[76:79]
	v_mfma_f32_16x16x32_bf16 v[72:75], v[168:171], v[216:219], v[72:75]
	v_mfma_f32_16x16x32_bf16 v[116:119], v[172:175], v[188:191], v[116:119]
	v_mfma_f32_16x16x32_bf16 v[112:115], v[180:183], v[188:191], v[112:115]
	v_mfma_f32_16x16x32_bf16 v[100:103], v[172:175], v[196:199], v[100:103]
	v_mfma_f32_16x16x32_bf16 v[96:99], v[180:183], v[196:199], v[96:99]
	v_mfma_f32_16x16x32_bf16 v[84:87], v[172:175], v[204:207], v[84:87]
	v_mfma_f32_16x16x32_bf16 v[80:83], v[180:183], v[204:207], v[80:83]
	v_mfma_f32_16x16x32_bf16 v[68:71], v[172:175], v[212:215], v[68:71]
	v_mfma_f32_16x16x32_bf16 v[64:67], v[180:183], v[212:215], v[64:67]
	v_mfma_f32_16x16x32_bf16 v[116:119], v[176:179], v[192:195], v[116:119]
	v_mfma_f32_16x16x32_bf16 v[112:115], v[184:187], v[192:195], v[112:115]
	v_mfma_f32_16x16x32_bf16 v[100:103], v[176:179], v[200:203], v[100:103]
	v_mfma_f32_16x16x32_bf16 v[96:99], v[184:187], v[200:203], v[96:99]
	v_mfma_f32_16x16x32_bf16 v[84:87], v[176:179], v[208:211], v[84:87]
	v_mfma_f32_16x16x32_bf16 v[80:83], v[184:187], v[208:211], v[80:83]
	v_mfma_f32_16x16x32_bf16 v[68:71], v[176:179], v[216:219], v[68:71]
	v_mfma_f32_16x16x32_bf16 v[64:67], v[184:187], v[216:219], v[64:67]
	s_barrier
	s_add_i32 s36, s65, s11
	v_lshl_add_u64 v[150:151], v[150:151], 0, s[14:15]
	s_mov_b32 m0, s36
	s_nop 0
	global_load_lds_dwordx4 v[150:151], off
	s_add_i32 m0, s36, 0x2000
	s_add_u32 s36, s40, 0x80080
	v_lshl_add_u64 v[150:151], v[220:221], 0, s[14:15]
	s_addc_u32 s37, s41, 0
	s_add_i32 s40, s66, s11
	global_load_lds_dwordx4 v[150:151], off
	v_lshl_add_u64 v[150:151], s[36:37], 0, v[130:131]
	s_mov_b32 m0, s40
	s_nop 0
	global_load_lds_dwordx4 v[150:151], off
	v_lshl_add_u64 v[150:151], s[36:37], 0, v[134:135]
	s_add_i32 m0, s40, 0x2000
	s_nop 0
	global_load_lds_dwordx4 v[150:151], off
	v_lshl_add_u64 v[150:151], v[222:223], 0, s[14:15]
	s_mov_b32 m0, s53
	s_nop 0
	global_load_lds_dwordx4 v[150:151], off
	v_lshl_add_u64 v[150:151], v[224:225], 0, s[14:15]
	s_mov_b32 m0, s54
	s_nop 0
	global_load_lds_dwordx4 v[150:151], off
	ds_read_b128 v[188:191], v158 offset:49152
	ds_read_b128 v[192:195], v158 offset:50176
	ds_read_b128 v[196:199], v158 offset:51200
	ds_read_b128 v[200:203], v158 offset:52224
	ds_read_b128 v[204:207], v158 offset:53248
	ds_read_b128 v[208:211], v158 offset:54272
	ds_read_b128 v[212:215], v158 offset:55296
	ds_read_b128 v[216:219], v158 offset:56320
	s_waitcnt vmcnt(8)
	s_waitcnt lgkmcnt(0)
	s_barrier
	s_waitcnt lgkmcnt(0)
	v_mfma_f32_16x16x32_bf16 v[60:63], v[146:149], v[188:191], v[60:63]
	v_mfma_f32_16x16x32_bf16 v[56:59], v[164:167], v[188:191], v[56:59]
	v_mfma_f32_16x16x32_bf16 v[44:47], v[146:149], v[196:199], v[44:47]
	v_mfma_f32_16x16x32_bf16 v[40:43], v[164:167], v[196:199], v[40:43]
	v_mfma_f32_16x16x32_bf16 v[28:31], v[146:149], v[204:207], v[28:31]
	v_mfma_f32_16x16x32_bf16 v[24:27], v[164:167], v[204:207], v[24:27]
	v_mfma_f32_16x16x32_bf16 v[12:15], v[146:149], v[212:215], v[12:15]
	v_mfma_f32_16x16x32_bf16 v[8:11], v[164:167], v[212:215], v[8:11]
	v_mfma_f32_16x16x32_bf16 v[60:63], v[160:163], v[192:195], v[60:63]
	v_mfma_f32_16x16x32_bf16 v[56:59], v[168:171], v[192:195], v[56:59]
	v_mfma_f32_16x16x32_bf16 v[44:47], v[160:163], v[200:203], v[44:47]
	v_mfma_f32_16x16x32_bf16 v[40:43], v[168:171], v[200:203], v[40:43]
	v_mfma_f32_16x16x32_bf16 v[28:31], v[160:163], v[208:211], v[28:31]
	v_mfma_f32_16x16x32_bf16 v[24:27], v[168:171], v[208:211], v[24:27]
	v_mfma_f32_16x16x32_bf16 v[12:15], v[160:163], v[216:219], v[12:15]
	v_mfma_f32_16x16x32_bf16 v[8:11], v[168:171], v[216:219], v[8:11]
	v_mfma_f32_16x16x32_bf16 v[52:55], v[172:175], v[188:191], v[52:55]
	v_mfma_f32_16x16x32_bf16 v[48:51], v[180:183], v[188:191], v[48:51]
	v_mfma_f32_16x16x32_bf16 v[36:39], v[172:175], v[196:199], v[36:39]
	v_mfma_f32_16x16x32_bf16 v[32:35], v[180:183], v[196:199], v[32:35]
	v_mfma_f32_16x16x32_bf16 v[20:23], v[172:175], v[204:207], v[20:23]
	v_mfma_f32_16x16x32_bf16 v[16:19], v[180:183], v[204:207], v[16:19]
	v_mfma_f32_16x16x32_bf16 v[4:7], v[172:175], v[212:215], v[4:7]
	v_mfma_f32_16x16x32_bf16 v[0:3], v[180:183], v[212:215], v[0:3]
	v_mfma_f32_16x16x32_bf16 v[52:55], v[176:179], v[192:195], v[52:55]
	v_mfma_f32_16x16x32_bf16 v[48:51], v[184:187], v[192:195], v[48:51]
	v_mfma_f32_16x16x32_bf16 v[36:39], v[176:179], v[200:203], v[36:39]
	v_mfma_f32_16x16x32_bf16 v[32:35], v[184:187], v[200:203], v[32:35]
	v_mfma_f32_16x16x32_bf16 v[20:23], v[176:179], v[208:211], v[20:23]
	v_mfma_f32_16x16x32_bf16 v[16:19], v[184:187], v[208:211], v[16:19]
	v_mfma_f32_16x16x32_bf16 v[4:7], v[176:179], v[216:219], v[4:7]
	v_mfma_f32_16x16x32_bf16 v[0:3], v[184:187], v[216:219], v[0:3]
	s_barrier
	s_add_i32 s64, s64, 2
	s_add_u32 s62, s62, 0x100
	s_addc_u32 s63, s63, 0
	s_cmp_gt_u32 s64, 29
	s_mov_b64 s[36:37], s[38:39]
	s_cbranch_scc0 .LBB0_387
	s_and_b64 vcc, exec, s[4:5]
	s_cbranch_vccnz .LBB0_392
	s_cmp_gt_i32 s59, 11
	s_mov_b64 s[36:37], -1
	s_cbranch_scc1 .LBB0_393

.Lgprio3:
.LBB0_1117:
	ds_read_b128 v[144:147], v159
	ds_read_b128 v[148:151], v159 offset:1024
	ds_read_b128 v[162:165], v159 offset:2048
	ds_read_b128 v[166:169], v159 offset:3072
	ds_read_b128 v[170:173], v160
	ds_read_b128 v[174:177], v160 offset:1024
	ds_read_b128 v[178:181], v160 offset:2048
	ds_read_b128 v[182:185], v160 offset:3072
	s_add_u32 s48, s46, 0xfff80080
	s_addc_u32 s49, s47, -1
	s_cmp_eq_u32 s63, 28
	s_cselect_b32 s51, s7, s49
	s_cselect_b32 s50, s11, s48
	s_cselect_b32 s49, s37, s62
	s_cselect_b32 s48, s39, s45
	v_lshl_add_u64 v[152:153], s[46:47], 0, v[136:137]
	s_add_i32 m0, s55, 0xc000
	s_nop 0
	global_load_lds_dwordx4 v[152:153], off
	v_lshl_add_u64 v[152:153], s[46:47], 0, v[138:139]
	s_add_i32 m0, s55, 0xe000
	s_nop 0
	global_load_lds_dwordx4 v[152:153], off
	ds_read_b128 v[186:189], v161
	ds_read_b128 v[190:193], v161 offset:1024
	ds_read_b128 v[194:197], v161 offset:2048
	ds_read_b128 v[198:201], v161 offset:3072
	ds_read_b128 v[202:205], v161 offset:4096
	ds_read_b128 v[206:209], v161 offset:5120
	ds_read_b128 v[210:213], v161 offset:6144
	ds_read_b128 v[214:217], v161 offset:7168
	s_waitcnt vmcnt(8)
	s_waitcnt lgkmcnt(0)
	s_barrier
	s_waitcnt lgkmcnt(0)
	v_mfma_f32_16x16x32_bf16 v[124:127], v[144:147], v[186:189], v[124:127]
	v_mfma_f32_16x16x32_bf16 v[120:123], v[162:165], v[186:189], v[120:123]
	v_mfma_f32_16x16x32_bf16 v[108:111], v[144:147], v[194:197], v[108:111]
	v_mfma_f32_16x16x32_bf16 v[104:107], v[162:165], v[194:197], v[104:107]
	v_mfma_f32_16x16x32_bf16 v[92:95], v[144:147], v[202:205], v[92:95]
	v_mfma_f32_16x16x32_bf16 v[88:91], v[162:165], v[202:205], v[88:91]
	v_mfma_f32_16x16x32_bf16 v[76:79], v[144:147], v[210:213], v[76:79]
	v_mfma_f32_16x16x32_bf16 v[72:75], v[162:165], v[210:213], v[72:75]
	v_mfma_f32_16x16x32_bf16 v[124:127], v[148:151], v[190:193], v[124:127]
	v_mfma_f32_16x16x32_bf16 v[120:123], v[166:169], v[190:193], v[120:123]
	v_mfma_f32_16x16x32_bf16 v[108:111], v[148:151], v[198:201], v[108:111]
	v_mfma_f32_16x16x32_bf16 v[104:107], v[166:169], v[198:201], v[104:107]
	v_mfma_f32_16x16x32_bf16 v[92:95], v[148:151], v[206:209], v[92:95]
	v_mfma_f32_16x16x32_bf16 v[88:91], v[166:169], v[206:209], v[88:91]
	v_mfma_f32_16x16x32_bf16 v[76:79], v[148:151], v[214:217], v[76:79]
	v_mfma_f32_16x16x32_bf16 v[72:75], v[166:169], v[214:217], v[72:75]
	v_mfma_f32_16x16x32_bf16 v[116:119], v[170:173], v[186:189], v[116:119]
	v_mfma_f32_16x16x32_bf16 v[112:115], v[178:181], v[186:189], v[112:115]
	v_mfma_f32_16x16x32_bf16 v[100:103], v[170:173], v[194:197], v[100:103]
	v_mfma_f32_16x16x32_bf16 v[96:99], v[178:181], v[194:197], v[96:99]
	v_mfma_f32_16x16x32_bf16 v[84:87], v[170:173], v[202:205], v[84:87]
	v_mfma_f32_16x16x32_bf16 v[80:83], v[178:181], v[202:205], v[80:83]
	v_mfma_f32_16x16x32_bf16 v[68:71], v[170:173], v[210:213], v[68:71]
	v_mfma_f32_16x16x32_bf16 v[64:67], v[178:181], v[210:213], v[64:67]
	v_mfma_f32_16x16x32_bf16 v[116:119], v[174:177], v[190:193], v[116:119]
	v_mfma_f32_16x16x32_bf16 v[112:115], v[182:185], v[190:193], v[112:115]
	v_mfma_f32_16x16x32_bf16 v[100:103], v[174:177], v[198:201], v[100:103]
	v_mfma_f32_16x16x32_bf16 v[96:99], v[182:185], v[198:201], v[96:99]
	v_mfma_f32_16x16x32_bf16 v[84:87], v[174:177], v[206:209], v[84:87]
	v_mfma_f32_16x16x32_bf16 v[80:83], v[182:185], v[206:209], v[80:83]
	v_mfma_f32_16x16x32_bf16 v[68:71], v[174:177], v[214:217], v[68:71]
	v_mfma_f32_16x16x32_bf16 v[64:67], v[182:185], v[214:217], v[64:67]
	s_barrier
	s_add_i32 s64, s60, s21
	v_lshl_add_u64 v[152:153], s[48:49], 0, v[130:131]
	s_mov_b32 m0, s64
	v_lshl_add_u64 v[218:219], s[48:49], 0, v[134:135]
	global_load_lds_dwordx4 v[152:153], off
	s_add_i32 m0, s64, 0x2000
	s_add_u32 s64, s48, 0x80000
	s_addc_u32 s65, s49, 0
	s_add_i32 s66, s61, s21
	global_load_lds_dwordx4 v[218:219], off
	v_lshl_add_u64 v[186:187], s[64:65], 0, v[130:131]
	s_mov_b32 m0, s66
	v_lshl_add_u64 v[220:221], s[50:51], 0, v[128:129]
	global_load_lds_dwordx4 v[186:187], off
	v_lshl_add_u64 v[186:187], s[64:65], 0, v[134:135]
	s_add_i32 m0, s66, 0x2000
	v_lshl_add_u64 v[222:223], s[50:51], 0, v[132:133]
	global_load_lds_dwordx4 v[186:187], off
	s_mov_b32 m0, s55
	s_nop 0
	global_load_lds_dwordx4 v[220:221], off
	s_mov_b32 m0, s56
	s_nop 0
	global_load_lds_dwordx4 v[222:223], off
	ds_read_b128 v[186:189], v161 offset:16384
	ds_read_b128 v[190:193], v161 offset:17408
	ds_read_b128 v[194:197], v161 offset:18432
	ds_read_b128 v[198:201], v161 offset:19456
	ds_read_b128 v[202:205], v161 offset:20480
	ds_read_b128 v[206:209], v161 offset:21504
	ds_read_b128 v[210:213], v161 offset:22528
	ds_read_b128 v[214:217], v161 offset:23552
	s_waitcnt vmcnt(8)
	s_waitcnt lgkmcnt(0)
	s_barrier
	s_waitcnt lgkmcnt(0)
	v_mfma_f32_16x16x32_bf16 v[60:63], v[144:147], v[186:189], v[60:63]
	v_mfma_f32_16x16x32_bf16 v[56:59], v[162:165], v[186:189], v[56:59]
	v_mfma_f32_16x16x32_bf16 v[44:47], v[144:147], v[194:197], v[44:47]
	v_mfma_f32_16x16x32_bf16 v[40:43], v[162:165], v[194:197], v[40:43]
	v_mfma_f32_16x16x32_bf16 v[28:31], v[144:147], v[202:205], v[28:31]
	v_mfma_f32_16x16x32_bf16 v[24:27], v[162:165], v[202:205], v[24:27]
	v_mfma_f32_16x16x32_bf16 v[12:15], v[144:147], v[210:213], v[12:15]
	v_mfma_f32_16x16x32_bf16 v[8:11], v[162:165], v[210:213], v[8:11]
	v_mfma_f32_16x16x32_bf16 v[60:63], v[148:151], v[190:193], v[60:63]
	v_mfma_f32_16x16x32_bf16 v[56:59], v[166:169], v[190:193], v[56:59]
	v_mfma_f32_16x16x32_bf16 v[44:47], v[148:151], v[198:201], v[44:47]
	v_mfma_f32_16x16x32_bf16 v[40:43], v[166:169], v[198:201], v[40:43]
	v_mfma_f32_16x16x32_bf16 v[28:31], v[148:151], v[206:209], v[28:31]
	v_mfma_f32_16x16x32_bf16 v[24:27], v[166:169], v[206:209], v[24:27]
	v_mfma_f32_16x16x32_bf16 v[12:15], v[148:151], v[214:217], v[12:15]
	v_mfma_f32_16x16x32_bf16 v[8:11], v[166:169], v[214:217], v[8:11]
	v_mfma_f32_16x16x32_bf16 v[52:55], v[170:173], v[186:189], v[52:55]
	v_mfma_f32_16x16x32_bf16 v[48:51], v[178:181], v[186:189], v[48:51]
	v_mfma_f32_16x16x32_bf16 v[36:39], v[170:173], v[194:197], v[36:39]
	v_mfma_f32_16x16x32_bf16 v[32:35], v[178:181], v[194:197], v[32:35]
	v_mfma_f32_16x16x32_bf16 v[20:23], v[170:173], v[202:205], v[20:23]
	v_mfma_f32_16x16x32_bf16 v[16:19], v[178:181], v[202:205], v[16:19]
	v_mfma_f32_16x16x32_bf16 v[4:7], v[170:173], v[210:213], v[4:7]
	v_mfma_f32_16x16x32_bf16 v[0:3], v[178:181], v[210:213], v[0:3]
	v_mfma_f32_16x16x32_bf16 v[52:55], v[174:177], v[190:193], v[52:55]
	v_mfma_f32_16x16x32_bf16 v[48:51], v[182:185], v[190:193], v[48:51]
	v_mfma_f32_16x16x32_bf16 v[36:39], v[174:177], v[198:201], v[36:39]
	v_mfma_f32_16x16x32_bf16 v[32:35], v[182:185], v[198:201], v[32:35]
	v_mfma_f32_16x16x32_bf16 v[20:23], v[174:177], v[206:209], v[20:23]
	v_mfma_f32_16x16x32_bf16 v[16:19], v[182:185], v[206:209], v[16:19]
	v_mfma_f32_16x16x32_bf16 v[4:7], v[174:177], v[214:217], v[4:7]
	v_mfma_f32_16x16x32_bf16 v[0:3], v[182:185], v[214:217], v[0:3]
	s_barrier
	s_add_i32 s64, 0, 0x18000
	s_add_i32 s65, 0, 0x1c000
	v_add_u32_e32 v166, s64, v154
	v_add_u32_e32 v182, s65, v154
	ds_read_b128 v[144:147], v166
	ds_read_b128 v[148:151], v166 offset:1024
	ds_read_b128 v[162:165], v166 offset:2048
	ds_read_b128 v[166:169], v166 offset:3072
	ds_read_b128 v[170:173], v182
	ds_read_b128 v[174:177], v182 offset:1024
	ds_read_b128 v[178:181], v182 offset:2048
	ds_read_b128 v[182:185], v182 offset:3072
	s_add_u32 s50, s50, 0x80000
	s_addc_u32 s51, s51, 0
	s_mov_b32 m0, s57
	v_lshl_add_u64 v[186:187], s[50:51], 0, v[128:129]
	global_load_lds_dwordx4 v[186:187], off
	v_lshl_add_u64 v[186:187], s[50:51], 0, v[132:133]
	s_mov_b32 m0, s58
	s_nop 0
	global_load_lds_dwordx4 v[186:187], off
	ds_read_b128 v[186:189], v161 offset:32768
	ds_read_b128 v[190:193], v161 offset:33792
	ds_read_b128 v[194:197], v161 offset:34816
	ds_read_b128 v[198:201], v161 offset:35840
	ds_read_b128 v[202:205], v161 offset:36864
	ds_read_b128 v[206:209], v161 offset:37888
	ds_read_b128 v[210:213], v161 offset:38912
	ds_read_b128 v[214:217], v161 offset:39936
	s_waitcnt vmcnt(8)
	s_waitcnt lgkmcnt(0)
	s_barrier
	s_waitcnt lgkmcnt(0)
	v_mfma_f32_16x16x32_bf16 v[124:127], v[144:147], v[186:189], v[124:127]
	v_mfma_f32_16x16x32_bf16 v[120:123], v[162:165], v[186:189], v[120:123]
	v_mfma_f32_16x16x32_bf16 v[108:111], v[144:147], v[194:197], v[108:111]
	v_mfma_f32_16x16x32_bf16 v[104:107], v[162:165], v[194:197], v[104:107]
	v_mfma_f32_16x16x32_bf16 v[92:95], v[144:147], v[202:205], v[92:95]
	v_mfma_f32_16x16x32_bf16 v[88:91], v[162:165], v[202:205], v[88:91]
	v_mfma_f32_16x16x32_bf16 v[76:79], v[144:147], v[210:213], v[76:79]
	v_mfma_f32_16x16x32_bf16 v[72:75], v[162:165], v[210:213], v[72:75]
	v_mfma_f32_16x16x32_bf16 v[124:127], v[148:151], v[190:193], v[124:127]
	v_mfma_f32_16x16x32_bf16 v[120:123], v[166:169], v[190:193], v[120:123]
	v_mfma_f32_16x16x32_bf16 v[108:111], v[148:151], v[198:201], v[108:111]
	v_mfma_f32_16x16x32_bf16 v[104:107], v[166:169], v[198:201], v[104:107]
	v_mfma_f32_16x16x32_bf16 v[92:95], v[148:151], v[206:209], v[92:95]
	v_mfma_f32_16x16x32_bf16 v[88:91], v[166:169], v[206:209], v[88:91]
	v_mfma_f32_16x16x32_bf16 v[76:79], v[148:151], v[214:217], v[76:79]
	v_mfma_f32_16x16x32_bf16 v[72:75], v[166:169], v[214:217], v[72:75]
	v_mfma_f32_16x16x32_bf16 v[116:119], v[170:173], v[186:189], v[116:119]
	v_mfma_f32_16x16x32_bf16 v[112:115], v[178:181], v[186:189], v[112:115]
	v_mfma_f32_16x16x32_bf16 v[100:103], v[170:173], v[194:197], v[100:103]
	v_mfma_f32_16x16x32_bf16 v[96:99], v[178:181], v[194:197], v[96:99]
	v_mfma_f32_16x16x32_bf16 v[84:87], v[170:173], v[202:205], v[84:87]
	v_mfma_f32_16x16x32_bf16 v[80:83], v[178:181], v[202:205], v[80:83]
	v_mfma_f32_16x16x32_bf16 v[68:71], v[170:173], v[210:213], v[68:71]
	v_mfma_f32_16x16x32_bf16 v[64:67], v[178:181], v[210:213], v[64:67]
	v_mfma_f32_16x16x32_bf16 v[116:119], v[174:177], v[190:193], v[116:119]
	v_mfma_f32_16x16x32_bf16 v[112:115], v[182:185], v[190:193], v[112:115]
	v_mfma_f32_16x16x32_bf16 v[100:103], v[174:177], v[198:201], v[100:103]
	v_mfma_f32_16x16x32_bf16 v[96:99], v[182:185], v[198:201], v[96:99]
	v_mfma_f32_16x16x32_bf16 v[84:87], v[174:177], v[206:209], v[84:87]
	v_mfma_f32_16x16x32_bf16 v[80:83], v[182:185], v[206:209], v[80:83]
	v_mfma_f32_16x16x32_bf16 v[68:71], v[174:177], v[214:217], v[68:71]
	v_mfma_f32_16x16x32_bf16 v[64:67], v[182:185], v[214:217], v[64:67]
	s_barrier
	s_add_i32 s50, s64, s21
	v_lshl_add_u64 v[152:153], v[152:153], 0, s[30:31]
	s_mov_b32 m0, s50
	s_nop 0
	global_load_lds_dwordx4 v[152:153], off
	s_add_i32 m0, s50, 0x2000
	s_add_u32 s48, s48, 0x80080
	v_lshl_add_u64 v[152:153], v[218:219], 0, s[30:31]
	s_addc_u32 s49, s49, 0
	s_add_i32 s50, s65, s21
	global_load_lds_dwordx4 v[152:153], off
	v_lshl_add_u64 v[152:153], s[48:49], 0, v[130:131]
	s_mov_b32 m0, s50
	s_nop 0
	global_load_lds_dwordx4 v[152:153], off
	v_lshl_add_u64 v[152:153], s[48:49], 0, v[134:135]
	s_add_i32 m0, s50, 0x2000
	s_nop 0
	global_load_lds_dwordx4 v[152:153], off
	v_lshl_add_u64 v[152:153], v[220:221], 0, s[30:31]
	s_mov_b32 m0, s26
	s_nop 0
	global_load_lds_dwordx4 v[152:153], off
	v_lshl_add_u64 v[152:153], v[222:223], 0, s[30:31]
	s_mov_b32 m0, s27
	s_nop 0
	global_load_lds_dwordx4 v[152:153], off
	ds_read_b128 v[186:189], v161 offset:49152
	ds_read_b128 v[190:193], v161 offset:50176
	ds_read_b128 v[194:197], v161 offset:51200
	ds_read_b128 v[198:201], v161 offset:52224
	ds_read_b128 v[202:205], v161 offset:53248
	ds_read_b128 v[206:209], v161 offset:54272
	ds_read_b128 v[210:213], v161 offset:55296
	ds_read_b128 v[214:217], v161 offset:56320
	s_waitcnt vmcnt(8)
	s_waitcnt lgkmcnt(0)
	s_barrier
	s_waitcnt lgkmcnt(0)
	v_mfma_f32_16x16x32_bf16 v[60:63], v[144:147], v[186:189], v[60:63]
	v_mfma_f32_16x16x32_bf16 v[56:59], v[162:165], v[186:189], v[56:59]
	v_mfma_f32_16x16x32_bf16 v[44:47], v[144:147], v[194:197], v[44:47]
	v_mfma_f32_16x16x32_bf16 v[40:43], v[162:165], v[194:197], v[40:43]
	v_mfma_f32_16x16x32_bf16 v[28:31], v[144:147], v[202:205], v[28:31]
	v_mfma_f32_16x16x32_bf16 v[24:27], v[162:165], v[202:205], v[24:27]
	v_mfma_f32_16x16x32_bf16 v[12:15], v[144:147], v[210:213], v[12:15]
	v_mfma_f32_16x16x32_bf16 v[8:11], v[162:165], v[210:213], v[8:11]
	v_mfma_f32_16x16x32_bf16 v[60:63], v[148:151], v[190:193], v[60:63]
	v_mfma_f32_16x16x32_bf16 v[56:59], v[166:169], v[190:193], v[56:59]
	v_mfma_f32_16x16x32_bf16 v[44:47], v[148:151], v[198:201], v[44:47]
	v_mfma_f32_16x16x32_bf16 v[40:43], v[166:169], v[198:201], v[40:43]
	v_mfma_f32_16x16x32_bf16 v[28:31], v[148:151], v[206:209], v[28:31]
	v_mfma_f32_16x16x32_bf16 v[24:27], v[166:169], v[206:209], v[24:27]
	v_mfma_f32_16x16x32_bf16 v[12:15], v[148:151], v[214:217], v[12:15]
	v_mfma_f32_16x16x32_bf16 v[8:11], v[166:169], v[214:217], v[8:11]
	v_mfma_f32_16x16x32_bf16 v[52:55], v[170:173], v[186:189], v[52:55]
	v_mfma_f32_16x16x32_bf16 v[48:51], v[178:181], v[186:189], v[48:51]
	v_mfma_f32_16x16x32_bf16 v[36:39], v[170:173], v[194:197], v[36:39]
	v_mfma_f32_16x16x32_bf16 v[32:35], v[178:181], v[194:197], v[32:35]
	v_mfma_f32_16x16x32_bf16 v[20:23], v[170:173], v[202:205], v[20:23]
	v_mfma_f32_16x16x32_bf16 v[16:19], v[178:181], v[202:205], v[16:19]
	v_mfma_f32_16x16x32_bf16 v[4:7], v[170:173], v[210:213], v[4:7]
	v_mfma_f32_16x16x32_bf16 v[0:3], v[178:181], v[210:213], v[0:3]
	v_mfma_f32_16x16x32_bf16 v[52:55], v[174:177], v[190:193], v[52:55]
	v_mfma_f32_16x16x32_bf16 v[48:51], v[182:185], v[190:193], v[48:51]
	v_mfma_f32_16x16x32_bf16 v[36:39], v[174:177], v[198:201], v[36:39]
	v_mfma_f32_16x16x32_bf16 v[32:35], v[182:185], v[198:201], v[32:35]
	v_mfma_f32_16x16x32_bf16 v[20:23], v[174:177], v[206:209], v[20:23]
	v_mfma_f32_16x16x32_bf16 v[16:19], v[182:185], v[206:209], v[16:19]
	v_mfma_f32_16x16x32_bf16 v[4:7], v[174:177], v[214:217], v[4:7]
	v_mfma_f32_16x16x32_bf16 v[0:3], v[182:185], v[214:217], v[0:3]
	s_barrier
	s_add_i32 s63, s63, 2
	s_add_u32 s46, s46, 0x100
	s_addc_u32 s47, s47, 0
	s_add_u32 s45, s45, 0x100
	s_addc_u32 s62, s62, 0
	s_cmp_gt_u32 s63, 29
	s_cbranch_scc0 .LBB0_1117
	s_and_b64 vcc, exec, s[16:17]
	s_cbranch_vccz .LBB0_1120
	s_barrier

.Lgprio4:
.LBB0_1240:
	ds_read_b128 v[144:147], v153
	ds_read_b128 v[158:161], v153 offset:1024
	ds_read_b128 v[162:165], v153 offset:2048
	ds_read_b128 v[166:169], v153 offset:3072
	ds_read_b128 v[170:173], v154
	ds_read_b128 v[174:177], v154 offset:1024
	ds_read_b128 v[178:181], v154 offset:2048
	ds_read_b128 v[182:185], v154 offset:3072
	s_add_u32 s40, s38, 0x100
	s_addc_u32 s41, s39, 0
	s_cmp_eq_u32 s61, 28
	s_cselect_b32 s45, s29, s41
	s_cselect_b32 s44, s57, s40
	s_cselect_b32 s43, s19, s60
	s_cselect_b32 s42, s58, s59
	v_lshl_add_u64 v[148:149], s[38:39], 0, v[136:137]
	s_add_i32 m0, s37, 0xc000
	s_nop 0
	global_load_lds_dwordx4 v[148:149], off
	v_lshl_add_u64 v[148:149], s[38:39], 0, v[138:139]
	s_add_i32 m0, s37, 0xe000
	s_nop 0
	global_load_lds_dwordx4 v[148:149], off
	ds_read_b128 v[186:189], v155
	ds_read_b128 v[190:193], v155 offset:1024
	ds_read_b128 v[194:197], v155 offset:2048
	ds_read_b128 v[198:201], v155 offset:3072
	ds_read_b128 v[202:205], v155 offset:4096
	ds_read_b128 v[206:209], v155 offset:5120
	ds_read_b128 v[210:213], v155 offset:6144
	ds_read_b128 v[214:217], v155 offset:7168
	s_waitcnt vmcnt(8)
	s_waitcnt lgkmcnt(0)
	s_barrier
	s_waitcnt lgkmcnt(0)
	v_mfma_f32_16x16x32_bf16 v[124:127], v[144:147], v[186:189], v[124:127]
	v_mfma_f32_16x16x32_bf16 v[120:123], v[162:165], v[186:189], v[120:123]
	v_mfma_f32_16x16x32_bf16 v[108:111], v[144:147], v[194:197], v[108:111]
	v_mfma_f32_16x16x32_bf16 v[104:107], v[162:165], v[194:197], v[104:107]
	v_mfma_f32_16x16x32_bf16 v[92:95], v[144:147], v[202:205], v[92:95]
	v_mfma_f32_16x16x32_bf16 v[88:91], v[162:165], v[202:205], v[88:91]
	v_mfma_f32_16x16x32_bf16 v[76:79], v[144:147], v[210:213], v[76:79]
	v_mfma_f32_16x16x32_bf16 v[72:75], v[162:165], v[210:213], v[72:75]
	v_mfma_f32_16x16x32_bf16 v[124:127], v[158:161], v[190:193], v[124:127]
	v_mfma_f32_16x16x32_bf16 v[120:123], v[166:169], v[190:193], v[120:123]
	v_mfma_f32_16x16x32_bf16 v[108:111], v[158:161], v[198:201], v[108:111]
	v_mfma_f32_16x16x32_bf16 v[104:107], v[166:169], v[198:201], v[104:107]
	v_mfma_f32_16x16x32_bf16 v[92:95], v[158:161], v[206:209], v[92:95]
	v_mfma_f32_16x16x32_bf16 v[88:91], v[166:169], v[206:209], v[88:91]
	v_mfma_f32_16x16x32_bf16 v[76:79], v[158:161], v[214:217], v[76:79]
	v_mfma_f32_16x16x32_bf16 v[72:75], v[166:169], v[214:217], v[72:75]
	v_mfma_f32_16x16x32_bf16 v[116:119], v[170:173], v[186:189], v[116:119]
	v_mfma_f32_16x16x32_bf16 v[112:115], v[178:181], v[186:189], v[112:115]
	v_mfma_f32_16x16x32_bf16 v[100:103], v[170:173], v[194:197], v[100:103]
	v_mfma_f32_16x16x32_bf16 v[96:99], v[178:181], v[194:197], v[96:99]
	v_mfma_f32_16x16x32_bf16 v[84:87], v[170:173], v[202:205], v[84:87]
	v_mfma_f32_16x16x32_bf16 v[80:83], v[178:181], v[202:205], v[80:83]
	v_mfma_f32_16x16x32_bf16 v[68:71], v[170:173], v[210:213], v[68:71]
	v_mfma_f32_16x16x32_bf16 v[64:67], v[178:181], v[210:213], v[64:67]
	v_mfma_f32_16x16x32_bf16 v[116:119], v[174:177], v[190:193], v[116:119]
	v_mfma_f32_16x16x32_bf16 v[112:115], v[182:185], v[190:193], v[112:115]
	v_mfma_f32_16x16x32_bf16 v[100:103], v[174:177], v[198:201], v[100:103]
	v_mfma_f32_16x16x32_bf16 v[96:99], v[182:185], v[198:201], v[96:99]
	v_mfma_f32_16x16x32_bf16 v[84:87], v[174:177], v[206:209], v[84:87]
	v_mfma_f32_16x16x32_bf16 v[80:83], v[182:185], v[206:209], v[80:83]
	v_mfma_f32_16x16x32_bf16 v[68:71], v[174:177], v[214:217], v[68:71]
	v_mfma_f32_16x16x32_bf16 v[64:67], v[182:185], v[214:217], v[64:67]
	s_barrier
	s_add_i32 s38, s54, s21
	v_lshl_add_u64 v[148:149], s[42:43], 0, v[132:133]
	s_mov_b32 m0, s38
	v_lshl_add_u64 v[218:219], s[42:43], 0, v[128:129]
	global_load_lds_dwordx4 v[148:149], off
	s_add_i32 m0, s38, 0x2000
	s_add_u32 s38, s42, 0x80000
	s_addc_u32 s39, s43, 0
	s_add_i32 s62, s55, s21
	global_load_lds_dwordx4 v[218:219], off
	v_lshl_add_u64 v[186:187], s[38:39], 0, v[132:133]
	s_mov_b32 m0, s62
	v_lshl_add_u64 v[220:221], s[44:45], 0, v[134:135]
	global_load_lds_dwordx4 v[186:187], off
	v_lshl_add_u64 v[186:187], s[38:39], 0, v[128:129]
	s_add_i32 m0, s62, 0x2000
	v_lshl_add_u64 v[222:223], s[44:45], 0, v[130:131]
	global_load_lds_dwordx4 v[186:187], off
	s_mov_b32 m0, s37
	s_nop 0
	global_load_lds_dwordx4 v[220:221], off
	s_mov_b32 m0, s47
	s_nop 0
	global_load_lds_dwordx4 v[222:223], off
	ds_read_b128 v[186:189], v155 offset:16384
	ds_read_b128 v[190:193], v155 offset:17408
	ds_read_b128 v[194:197], v155 offset:18432
	ds_read_b128 v[198:201], v155 offset:19456
	ds_read_b128 v[202:205], v155 offset:20480
	ds_read_b128 v[206:209], v155 offset:21504
	ds_read_b128 v[210:213], v155 offset:22528
	ds_read_b128 v[214:217], v155 offset:23552
	s_waitcnt vmcnt(8)
	s_waitcnt lgkmcnt(0)
	s_barrier
	s_waitcnt lgkmcnt(0)
	v_mfma_f32_16x16x32_bf16 v[60:63], v[144:147], v[186:189], v[60:63]
	v_mfma_f32_16x16x32_bf16 v[56:59], v[162:165], v[186:189], v[56:59]
	v_mfma_f32_16x16x32_bf16 v[44:47], v[144:147], v[194:197], v[44:47]
	v_mfma_f32_16x16x32_bf16 v[40:43], v[162:165], v[194:197], v[40:43]
	v_mfma_f32_16x16x32_bf16 v[28:31], v[144:147], v[202:205], v[28:31]
	v_mfma_f32_16x16x32_bf16 v[24:27], v[162:165], v[202:205], v[24:27]
	v_mfma_f32_16x16x32_bf16 v[12:15], v[144:147], v[210:213], v[12:15]
	v_mfma_f32_16x16x32_bf16 v[8:11], v[162:165], v[210:213], v[8:11]
	v_mfma_f32_16x16x32_bf16 v[60:63], v[158:161], v[190:193], v[60:63]
	v_mfma_f32_16x16x32_bf16 v[56:59], v[166:169], v[190:193], v[56:59]
	v_mfma_f32_16x16x32_bf16 v[44:47], v[158:161], v[198:201], v[44:47]
	v_mfma_f32_16x16x32_bf16 v[40:43], v[166:169], v[198:201], v[40:43]
	v_mfma_f32_16x16x32_bf16 v[28:31], v[158:161], v[206:209], v[28:31]
	v_mfma_f32_16x16x32_bf16 v[24:27], v[166:169], v[206:209], v[24:27]
	v_mfma_f32_16x16x32_bf16 v[12:15], v[158:161], v[214:217], v[12:15]
	v_mfma_f32_16x16x32_bf16 v[8:11], v[166:169], v[214:217], v[8:11]
	v_mfma_f32_16x16x32_bf16 v[52:55], v[170:173], v[186:189], v[52:55]
	v_mfma_f32_16x16x32_bf16 v[48:51], v[178:181], v[186:189], v[48:51]
	v_mfma_f32_16x16x32_bf16 v[36:39], v[170:173], v[194:197], v[36:39]
	v_mfma_f32_16x16x32_bf16 v[32:35], v[178:181], v[194:197], v[32:35]
	v_mfma_f32_16x16x32_bf16 v[20:23], v[170:173], v[202:205], v[20:23]
	v_mfma_f32_16x16x32_bf16 v[16:19], v[178:181], v[202:205], v[16:19]
	v_mfma_f32_16x16x32_bf16 v[4:7], v[170:173], v[210:213], v[4:7]
	v_mfma_f32_16x16x32_bf16 v[0:3], v[178:181], v[210:213], v[0:3]
	v_mfma_f32_16x16x32_bf16 v[52:55], v[174:177], v[190:193], v[52:55]
	v_mfma_f32_16x16x32_bf16 v[48:51], v[182:185], v[190:193], v[48:51]
	v_mfma_f32_16x16x32_bf16 v[36:39], v[174:177], v[198:201], v[36:39]
	v_mfma_f32_16x16x32_bf16 v[32:35], v[182:185], v[198:201], v[32:35]
	v_mfma_f32_16x16x32_bf16 v[20:23], v[174:177], v[206:209], v[20:23]
	v_mfma_f32_16x16x32_bf16 v[16:19], v[182:185], v[206:209], v[16:19]
	v_mfma_f32_16x16x32_bf16 v[4:7], v[174:177], v[214:217], v[4:7]
	v_mfma_f32_16x16x32_bf16 v[0:3], v[182:185], v[214:217], v[0:3]
	s_barrier
	s_add_i32 s62, 0, 0x18000
	v_add_u32_e32 v157, s62, v150
	s_add_i32 s63, 0, 0x1c000
	ds_read_b128 v[144:147], v157
	ds_read_b128 v[158:161], v157 offset:1024
	ds_read_b128 v[162:165], v157 offset:2048
	ds_read_b128 v[166:169], v157 offset:3072
	v_add_u32_e32 v157, s63, v150
	ds_read_b128 v[170:173], v157
	ds_read_b128 v[174:177], v157 offset:1024
	ds_read_b128 v[178:181], v157 offset:2048
	ds_read_b128 v[182:185], v157 offset:3072
	s_add_u32 s38, s44, 0x80000
	s_addc_u32 s39, s45, 0
	s_mov_b32 m0, s48
	v_lshl_add_u64 v[186:187], s[38:39], 0, v[134:135]
	global_load_lds_dwordx4 v[186:187], off
	v_lshl_add_u64 v[186:187], s[38:39], 0, v[130:131]
	s_mov_b32 m0, s49
	s_nop 0
	global_load_lds_dwordx4 v[186:187], off
	ds_read_b128 v[186:189], v155 offset:32768
	ds_read_b128 v[190:193], v155 offset:33792
	ds_read_b128 v[194:197], v155 offset:34816
	ds_read_b128 v[198:201], v155 offset:35840
	ds_read_b128 v[202:205], v155 offset:36864
	ds_read_b128 v[206:209], v155 offset:37888
	ds_read_b128 v[210:213], v155 offset:38912
	ds_read_b128 v[214:217], v155 offset:39936
	s_waitcnt vmcnt(8)
	s_waitcnt lgkmcnt(0)
	s_barrier
	s_waitcnt lgkmcnt(0)
	v_mfma_f32_16x16x32_bf16 v[124:127], v[144:147], v[186:189], v[124:127]
	v_mfma_f32_16x16x32_bf16 v[120:123], v[162:165], v[186:189], v[120:123]
	v_mfma_f32_16x16x32_bf16 v[108:111], v[144:147], v[194:197], v[108:111]
	v_mfma_f32_16x16x32_bf16 v[104:107], v[162:165], v[194:197], v[104:107]
	v_mfma_f32_16x16x32_bf16 v[92:95], v[144:147], v[202:205], v[92:95]
	v_mfma_f32_16x16x32_bf16 v[88:91], v[162:165], v[202:205], v[88:91]
	v_mfma_f32_16x16x32_bf16 v[76:79], v[144:147], v[210:213], v[76:79]
	v_mfma_f32_16x16x32_bf16 v[72:75], v[162:165], v[210:213], v[72:75]
	v_mfma_f32_16x16x32_bf16 v[124:127], v[158:161], v[190:193], v[124:127]
	v_mfma_f32_16x16x32_bf16 v[120:123], v[166:169], v[190:193], v[120:123]
	v_mfma_f32_16x16x32_bf16 v[108:111], v[158:161], v[198:201], v[108:111]
	v_mfma_f32_16x16x32_bf16 v[104:107], v[166:169], v[198:201], v[104:107]
	v_mfma_f32_16x16x32_bf16 v[92:95], v[158:161], v[206:209], v[92:95]
	v_mfma_f32_16x16x32_bf16 v[88:91], v[166:169], v[206:209], v[88:91]
	v_mfma_f32_16x16x32_bf16 v[76:79], v[158:161], v[214:217], v[76:79]
	v_mfma_f32_16x16x32_bf16 v[72:75], v[166:169], v[214:217], v[72:75]
	v_mfma_f32_16x16x32_bf16 v[116:119], v[170:173], v[186:189], v[116:119]
	v_mfma_f32_16x16x32_bf16 v[112:115], v[178:181], v[186:189], v[112:115]
	v_mfma_f32_16x16x32_bf16 v[100:103], v[170:173], v[194:197], v[100:103]
	v_mfma_f32_16x16x32_bf16 v[96:99], v[178:181], v[194:197], v[96:99]
	v_mfma_f32_16x16x32_bf16 v[84:87], v[170:173], v[202:205], v[84:87]
	v_mfma_f32_16x16x32_bf16 v[80:83], v[178:181], v[202:205], v[80:83]
	v_mfma_f32_16x16x32_bf16 v[68:71], v[170:173], v[210:213], v[68:71]
	v_mfma_f32_16x16x32_bf16 v[64:67], v[178:181], v[210:213], v[64:67]
	v_mfma_f32_16x16x32_bf16 v[116:119], v[174:177], v[190:193], v[116:119]
	v_mfma_f32_16x16x32_bf16 v[112:115], v[182:185], v[190:193], v[112:115]
	v_mfma_f32_16x16x32_bf16 v[100:103], v[174:177], v[198:201], v[100:103]
	v_mfma_f32_16x16x32_bf16 v[96:99], v[182:185], v[198:201], v[96:99]
	v_mfma_f32_16x16x32_bf16 v[84:87], v[174:177], v[206:209], v[84:87]
	v_mfma_f32_16x16x32_bf16 v[80:83], v[182:185], v[206:209], v[80:83]
	v_mfma_f32_16x16x32_bf16 v[68:71], v[174:177], v[214:217], v[68:71]
	v_mfma_f32_16x16x32_bf16 v[64:67], v[182:185], v[214:217], v[64:67]
	s_barrier
	s_add_i32 s38, s62, s21
	v_lshl_add_u64 v[148:149], v[148:149], 0, s[16:17]
	s_mov_b32 m0, s38
	s_nop 0
	global_load_lds_dwordx4 v[148:149], off
	s_add_i32 m0, s38, 0x2000
	s_add_u32 s38, s42, 0x80080
	v_lshl_add_u64 v[148:149], v[218:219], 0, s[16:17]
	s_addc_u32 s39, s43, 0
	s_add_i32 s42, s63, s21
	global_load_lds_dwordx4 v[148:149], off
	v_lshl_add_u64 v[148:149], s[38:39], 0, v[132:133]
	s_mov_b32 m0, s42
	s_nop 0
	global_load_lds_dwordx4 v[148:149], off
	v_lshl_add_u64 v[148:149], s[38:39], 0, v[128:129]
	s_add_i32 m0, s42, 0x2000
	s_nop 0
	global_load_lds_dwordx4 v[148:149], off
	v_lshl_add_u64 v[148:149], v[220:221], 0, s[16:17]
	s_mov_b32 m0, s51
	s_nop 0
	global_load_lds_dwordx4 v[148:149], off
	v_lshl_add_u64 v[148:149], v[222:223], 0, s[16:17]
	s_mov_b32 m0, s52
	s_nop 0
	global_load_lds_dwordx4 v[148:149], off
	ds_read_b128 v[186:189], v155 offset:49152
	ds_read_b128 v[190:193], v155 offset:50176
	ds_read_b128 v[194:197], v155 offset:51200
	ds_read_b128 v[198:201], v155 offset:52224
	ds_read_b128 v[202:205], v155 offset:53248
	ds_read_b128 v[206:209], v155 offset:54272
	ds_read_b128 v[210:213], v155 offset:55296
	ds_read_b128 v[214:217], v155 offset:56320
	s_waitcnt vmcnt(8)
	s_waitcnt lgkmcnt(0)
	s_barrier
	s_waitcnt lgkmcnt(0)
	v_mfma_f32_16x16x32_bf16 v[60:63], v[144:147], v[186:189], v[60:63]
	v_mfma_f32_16x16x32_bf16 v[56:59], v[162:165], v[186:189], v[56:59]
	v_mfma_f32_16x16x32_bf16 v[44:47], v[144:147], v[194:197], v[44:47]
	v_mfma_f32_16x16x32_bf16 v[40:43], v[162:165], v[194:197], v[40:43]
	v_mfma_f32_16x16x32_bf16 v[28:31], v[144:147], v[202:205], v[28:31]
	v_mfma_f32_16x16x32_bf16 v[24:27], v[162:165], v[202:205], v[24:27]
	v_mfma_f32_16x16x32_bf16 v[12:15], v[144:147], v[210:213], v[12:15]
	v_mfma_f32_16x16x32_bf16 v[8:11], v[162:165], v[210:213], v[8:11]
	v_mfma_f32_16x16x32_bf16 v[60:63], v[158:161], v[190:193], v[60:63]
	v_mfma_f32_16x16x32_bf16 v[56:59], v[166:169], v[190:193], v[56:59]
	v_mfma_f32_16x16x32_bf16 v[44:47], v[158:161], v[198:201], v[44:47]
	v_mfma_f32_16x16x32_bf16 v[40:43], v[166:169], v[198:201], v[40:43]
	v_mfma_f32_16x16x32_bf16 v[28:31], v[158:161], v[206:209], v[28:31]
	v_mfma_f32_16x16x32_bf16 v[24:27], v[166:169], v[206:209], v[24:27]
	v_mfma_f32_16x16x32_bf16 v[12:15], v[158:161], v[214:217], v[12:15]
	v_mfma_f32_16x16x32_bf16 v[8:11], v[166:169], v[214:217], v[8:11]
	v_mfma_f32_16x16x32_bf16 v[52:55], v[170:173], v[186:189], v[52:55]
	v_mfma_f32_16x16x32_bf16 v[48:51], v[178:181], v[186:189], v[48:51]
	v_mfma_f32_16x16x32_bf16 v[36:39], v[170:173], v[194:197], v[36:39]
	v_mfma_f32_16x16x32_bf16 v[32:35], v[178:181], v[194:197], v[32:35]
	v_mfma_f32_16x16x32_bf16 v[20:23], v[170:173], v[202:205], v[20:23]
	v_mfma_f32_16x16x32_bf16 v[16:19], v[178:181], v[202:205], v[16:19]
	v_mfma_f32_16x16x32_bf16 v[4:7], v[170:173], v[210:213], v[4:7]
	v_mfma_f32_16x16x32_bf16 v[0:3], v[178:181], v[210:213], v[0:3]
	v_mfma_f32_16x16x32_bf16 v[52:55], v[174:177], v[190:193], v[52:55]
	v_mfma_f32_16x16x32_bf16 v[48:51], v[182:185], v[190:193], v[48:51]
	v_mfma_f32_16x16x32_bf16 v[36:39], v[174:177], v[198:201], v[36:39]
	v_mfma_f32_16x16x32_bf16 v[32:35], v[182:185], v[198:201], v[32:35]
	v_mfma_f32_16x16x32_bf16 v[20:23], v[174:177], v[206:209], v[20:23]
	v_mfma_f32_16x16x32_bf16 v[16:19], v[182:185], v[206:209], v[16:19]
	v_mfma_f32_16x16x32_bf16 v[4:7], v[174:177], v[214:217], v[4:7]
	v_mfma_f32_16x16x32_bf16 v[0:3], v[182:185], v[214:217], v[0:3]
	s_barrier
	s_add_i32 s61, s61, 2
	s_add_u32 s59, s59, 0x100
	s_addc_u32 s60, s60, 0
	s_cmp_gt_u32 s61, 29
	s_mov_b64 s[38:39], s[40:41]
	s_cbranch_scc0 .LBB0_1240
	s_and_b64 vcc, exec, s[6:7]
	s_cbranch_vccz .LBB0_1243
	s_barrier

.Lgprio5:
.LBB0_1327:
	ds_read_b128 v[144:147], v151
	ds_read_b128 v[154:157], v151 offset:1024
	ds_read_b128 v[158:161], v151 offset:2048
	ds_read_b128 v[162:165], v151 offset:3072
	ds_read_b128 v[166:169], v152
	ds_read_b128 v[170:173], v152 offset:1024
	ds_read_b128 v[174:177], v152 offset:2048
	ds_read_b128 v[178:181], v152 offset:3072
	s_add_u32 s34, s30, 0x100
	s_addc_u32 s35, s31, 0
	s_cmpk_eq_i32 s55, 0x54
	s_cselect_b32 s39, s5, s35
	s_cselect_b32 s38, s4, s34
	s_cselect_b32 s37, s29, s54
	s_cselect_b32 s36, s28, s53
	v_lshl_add_u64 v[182:183], s[30:31], 0, v[136:137]
	s_add_i32 m0, s40, 0xc000
	s_nop 0
	global_load_lds_dwordx4 v[182:183], off
	v_lshl_add_u64 v[182:183], s[30:31], 0, v[138:139]
	s_add_i32 m0, s40, 0xe000
	s_nop 0
	global_load_lds_dwordx4 v[182:183], off
	ds_read_b128 v[182:185], v153
	ds_read_b128 v[186:189], v153 offset:1024
	ds_read_b128 v[190:193], v153 offset:2048
	ds_read_b128 v[194:197], v153 offset:3072
	ds_read_b128 v[198:201], v153 offset:4096
	ds_read_b128 v[202:205], v153 offset:5120
	ds_read_b128 v[206:209], v153 offset:6144
	ds_read_b128 v[210:213], v153 offset:7168
	s_waitcnt vmcnt(8)
	s_waitcnt lgkmcnt(0)
	s_barrier
	s_waitcnt lgkmcnt(0)
	v_mfma_f32_16x16x32_bf16 v[124:127], v[144:147], v[182:185], v[124:127]
	v_mfma_f32_16x16x32_bf16 v[120:123], v[158:161], v[182:185], v[120:123]
	v_mfma_f32_16x16x32_bf16 v[108:111], v[144:147], v[190:193], v[108:111]
	v_mfma_f32_16x16x32_bf16 v[104:107], v[158:161], v[190:193], v[104:107]
	v_mfma_f32_16x16x32_bf16 v[92:95], v[144:147], v[198:201], v[92:95]
	v_mfma_f32_16x16x32_bf16 v[88:91], v[158:161], v[198:201], v[88:91]
	v_mfma_f32_16x16x32_bf16 v[76:79], v[144:147], v[206:209], v[76:79]
	v_mfma_f32_16x16x32_bf16 v[72:75], v[158:161], v[206:209], v[72:75]
	v_mfma_f32_16x16x32_bf16 v[124:127], v[154:157], v[186:189], v[124:127]
	v_mfma_f32_16x16x32_bf16 v[120:123], v[162:165], v[186:189], v[120:123]
	v_mfma_f32_16x16x32_bf16 v[108:111], v[154:157], v[194:197], v[108:111]
	v_mfma_f32_16x16x32_bf16 v[104:107], v[162:165], v[194:197], v[104:107]
	v_mfma_f32_16x16x32_bf16 v[92:95], v[154:157], v[202:205], v[92:95]
	v_mfma_f32_16x16x32_bf16 v[88:91], v[162:165], v[202:205], v[88:91]
	v_mfma_f32_16x16x32_bf16 v[76:79], v[154:157], v[210:213], v[76:79]
	v_mfma_f32_16x16x32_bf16 v[72:75], v[162:165], v[210:213], v[72:75]
	v_mfma_f32_16x16x32_bf16 v[116:119], v[166:169], v[182:185], v[116:119]
	v_mfma_f32_16x16x32_bf16 v[112:115], v[174:177], v[182:185], v[112:115]
	v_mfma_f32_16x16x32_bf16 v[100:103], v[166:169], v[190:193], v[100:103]
	v_mfma_f32_16x16x32_bf16 v[96:99], v[174:177], v[190:193], v[96:99]
	v_mfma_f32_16x16x32_bf16 v[84:87], v[166:169], v[198:201], v[84:87]
	v_mfma_f32_16x16x32_bf16 v[80:83], v[174:177], v[198:201], v[80:83]
	v_mfma_f32_16x16x32_bf16 v[68:71], v[166:169], v[206:209], v[68:71]
	v_mfma_f32_16x16x32_bf16 v[64:67], v[174:177], v[206:209], v[64:67]
	v_mfma_f32_16x16x32_bf16 v[116:119], v[170:173], v[186:189], v[116:119]
	v_mfma_f32_16x16x32_bf16 v[112:115], v[178:181], v[186:189], v[112:115]
	v_mfma_f32_16x16x32_bf16 v[100:103], v[170:173], v[194:197], v[100:103]
	v_mfma_f32_16x16x32_bf16 v[96:99], v[178:181], v[194:197], v[96:99]
	v_mfma_f32_16x16x32_bf16 v[84:87], v[170:173], v[202:205], v[84:87]
	v_mfma_f32_16x16x32_bf16 v[80:83], v[178:181], v[202:205], v[80:83]
	v_mfma_f32_16x16x32_bf16 v[68:71], v[170:173], v[210:213], v[68:71]
	v_mfma_f32_16x16x32_bf16 v[64:67], v[178:181], v[210:213], v[64:67]
	s_barrier
	s_add_i32 s30, s48, s23
	v_lshl_add_u64 v[214:215], s[36:37], 0, v[130:131]
	s_mov_b32 m0, s30
	v_lshl_add_u64 v[216:217], s[36:37], 0, v[134:135]
	global_load_lds_dwordx4 v[214:215], off
	s_add_i32 m0, s30, 0x2000
	s_add_u32 s30, s36, 0x160000
	s_addc_u32 s31, s37, 0
	s_add_i32 s56, s49, s23
	global_load_lds_dwordx4 v[216:217], off
	v_lshl_add_u64 v[182:183], s[30:31], 0, v[130:131]
	s_mov_b32 m0, s56
	v_lshl_add_u64 v[218:219], s[38:39], 0, v[128:129]
	global_load_lds_dwordx4 v[182:183], off
	v_lshl_add_u64 v[182:183], s[30:31], 0, v[134:135]
	s_add_i32 m0, s56, 0x2000
	v_lshl_add_u64 v[220:221], s[38:39], 0, v[132:133]
	global_load_lds_dwordx4 v[182:183], off
	s_mov_b32 m0, s40
	s_nop 0
	global_load_lds_dwordx4 v[218:219], off
	s_mov_b32 m0, s41
	s_nop 0
	global_load_lds_dwordx4 v[220:221], off
	ds_read_b128 v[182:185], v153 offset:16384
	ds_read_b128 v[186:189], v153 offset:17408
	ds_read_b128 v[190:193], v153 offset:18432
	ds_read_b128 v[194:197], v153 offset:19456
	ds_read_b128 v[198:201], v153 offset:20480
	ds_read_b128 v[202:205], v153 offset:21504
	ds_read_b128 v[206:209], v153 offset:22528
	ds_read_b128 v[210:213], v153 offset:23552
	s_waitcnt vmcnt(8)
	s_waitcnt lgkmcnt(0)
	s_barrier
	s_waitcnt lgkmcnt(0)
	v_mfma_f32_16x16x32_bf16 v[60:63], v[144:147], v[182:185], v[60:63]
	v_mfma_f32_16x16x32_bf16 v[56:59], v[158:161], v[182:185], v[56:59]
	v_mfma_f32_16x16x32_bf16 v[44:47], v[144:147], v[190:193], v[44:47]
	v_mfma_f32_16x16x32_bf16 v[40:43], v[158:161], v[190:193], v[40:43]
	v_mfma_f32_16x16x32_bf16 v[28:31], v[144:147], v[198:201], v[28:31]
	v_mfma_f32_16x16x32_bf16 v[24:27], v[158:161], v[198:201], v[24:27]
	v_mfma_f32_16x16x32_bf16 v[12:15], v[144:147], v[206:209], v[12:15]
	v_mfma_f32_16x16x32_bf16 v[8:11], v[158:161], v[206:209], v[8:11]
	v_mfma_f32_16x16x32_bf16 v[60:63], v[154:157], v[186:189], v[60:63]
	v_mfma_f32_16x16x32_bf16 v[56:59], v[162:165], v[186:189], v[56:59]
	v_mfma_f32_16x16x32_bf16 v[44:47], v[154:157], v[194:197], v[44:47]
	v_mfma_f32_16x16x32_bf16 v[40:43], v[162:165], v[194:197], v[40:43]
	v_mfma_f32_16x16x32_bf16 v[28:31], v[154:157], v[202:205], v[28:31]
	v_mfma_f32_16x16x32_bf16 v[24:27], v[162:165], v[202:205], v[24:27]
	v_mfma_f32_16x16x32_bf16 v[12:15], v[154:157], v[210:213], v[12:15]
	v_mfma_f32_16x16x32_bf16 v[8:11], v[162:165], v[210:213], v[8:11]
	v_mfma_f32_16x16x32_bf16 v[52:55], v[166:169], v[182:185], v[52:55]
	v_mfma_f32_16x16x32_bf16 v[48:51], v[174:177], v[182:185], v[48:51]
	v_mfma_f32_16x16x32_bf16 v[36:39], v[166:169], v[190:193], v[36:39]
	v_mfma_f32_16x16x32_bf16 v[32:35], v[174:177], v[190:193], v[32:35]
	v_mfma_f32_16x16x32_bf16 v[20:23], v[166:169], v[198:201], v[20:23]
	v_mfma_f32_16x16x32_bf16 v[16:19], v[174:177], v[198:201], v[16:19]
	v_mfma_f32_16x16x32_bf16 v[4:7], v[166:169], v[206:209], v[4:7]
	v_mfma_f32_16x16x32_bf16 v[0:3], v[174:177], v[206:209], v[0:3]
	v_mfma_f32_16x16x32_bf16 v[52:55], v[170:173], v[186:189], v[52:55]
	v_mfma_f32_16x16x32_bf16 v[48:51], v[178:181], v[186:189], v[48:51]
	v_mfma_f32_16x16x32_bf16 v[36:39], v[170:173], v[194:197], v[36:39]
	v_mfma_f32_16x16x32_bf16 v[32:35], v[178:181], v[194:197], v[32:35]
	v_mfma_f32_16x16x32_bf16 v[20:23], v[170:173], v[202:205], v[20:23]
	v_mfma_f32_16x16x32_bf16 v[16:19], v[178:181], v[202:205], v[16:19]
	v_mfma_f32_16x16x32_bf16 v[4:7], v[170:173], v[210:213], v[4:7]
	v_mfma_f32_16x16x32_bf16 v[0:3], v[178:181], v[210:213], v[0:3]
	s_barrier
	s_add_i32 s56, 0, 0x18000
	s_add_i32 s57, 0, 0x1c000
	v_add_u32_e32 v162, s56, v148
	v_add_u32_e32 v178, s57, v148
	ds_read_b128 v[144:147], v162
	ds_read_b128 v[154:157], v162 offset:1024
	ds_read_b128 v[158:161], v162 offset:2048
	ds_read_b128 v[162:165], v162 offset:3072
	ds_read_b128 v[166:169], v178
	ds_read_b128 v[170:173], v178 offset:1024
	ds_read_b128 v[174:177], v178 offset:2048
	ds_read_b128 v[178:181], v178 offset:3072
	s_add_u32 s30, s38, 0x160000
	s_addc_u32 s31, s39, 0
	s_mov_b32 m0, s42
	v_lshl_add_u64 v[182:183], s[30:31], 0, v[128:129]
	global_load_lds_dwordx4 v[182:183], off
	v_lshl_add_u64 v[182:183], s[30:31], 0, v[132:133]
	s_mov_b32 m0, s43
	s_nop 0
	global_load_lds_dwordx4 v[182:183], off
	ds_read_b128 v[182:185], v153 offset:32768
	ds_read_b128 v[186:189], v153 offset:33792
	ds_read_b128 v[190:193], v153 offset:34816
	ds_read_b128 v[194:197], v153 offset:35840
	ds_read_b128 v[198:201], v153 offset:36864
	ds_read_b128 v[202:205], v153 offset:37888
	ds_read_b128 v[206:209], v153 offset:38912
	ds_read_b128 v[210:213], v153 offset:39936
	s_waitcnt vmcnt(8)
	s_waitcnt lgkmcnt(0)
	s_barrier
	s_waitcnt lgkmcnt(0)
	v_mfma_f32_16x16x32_bf16 v[124:127], v[144:147], v[182:185], v[124:127]
	v_mfma_f32_16x16x32_bf16 v[120:123], v[158:161], v[182:185], v[120:123]
	v_mfma_f32_16x16x32_bf16 v[108:111], v[144:147], v[190:193], v[108:111]
	v_mfma_f32_16x16x32_bf16 v[104:107], v[158:161], v[190:193], v[104:107]
	v_mfma_f32_16x16x32_bf16 v[92:95], v[144:147], v[198:201], v[92:95]
	v_mfma_f32_16x16x32_bf16 v[88:91], v[158:161], v[198:201], v[88:91]
	v_mfma_f32_16x16x32_bf16 v[76:79], v[144:147], v[206:209], v[76:79]
	v_mfma_f32_16x16x32_bf16 v[72:75], v[158:161], v[206:209], v[72:75]
	v_mfma_f32_16x16x32_bf16 v[124:127], v[154:157], v[186:189], v[124:127]
	v_mfma_f32_16x16x32_bf16 v[120:123], v[162:165], v[186:189], v[120:123]
	v_mfma_f32_16x16x32_bf16 v[108:111], v[154:157], v[194:197], v[108:111]
	v_mfma_f32_16x16x32_bf16 v[104:107], v[162:165], v[194:197], v[104:107]
	v_mfma_f32_16x16x32_bf16 v[92:95], v[154:157], v[202:205], v[92:95]
	v_mfma_f32_16x16x32_bf16 v[88:91], v[162:165], v[202:205], v[88:91]
	v_mfma_f32_16x16x32_bf16 v[76:79], v[154:157], v[210:213], v[76:79]
	v_mfma_f32_16x16x32_bf16 v[72:75], v[162:165], v[210:213], v[72:75]
	v_mfma_f32_16x16x32_bf16 v[116:119], v[166:169], v[182:185], v[116:119]
	v_mfma_f32_16x16x32_bf16 v[112:115], v[174:177], v[182:185], v[112:115]
	v_mfma_f32_16x16x32_bf16 v[100:103], v[166:169], v[190:193], v[100:103]
	v_mfma_f32_16x16x32_bf16 v[96:99], v[174:177], v[190:193], v[96:99]
	v_mfma_f32_16x16x32_bf16 v[84:87], v[166:169], v[198:201], v[84:87]
	v_mfma_f32_16x16x32_bf16 v[80:83], v[174:177], v[198:201], v[80:83]
	v_mfma_f32_16x16x32_bf16 v[68:71], v[166:169], v[206:209], v[68:71]
	v_mfma_f32_16x16x32_bf16 v[64:67], v[174:177], v[206:209], v[64:67]
	v_mfma_f32_16x16x32_bf16 v[116:119], v[170:173], v[186:189], v[116:119]
	v_mfma_f32_16x16x32_bf16 v[112:115], v[178:181], v[186:189], v[112:115]
	v_mfma_f32_16x16x32_bf16 v[100:103], v[170:173], v[194:197], v[100:103]
	v_mfma_f32_16x16x32_bf16 v[96:99], v[178:181], v[194:197], v[96:99]
	v_mfma_f32_16x16x32_bf16 v[84:87], v[170:173], v[202:205], v[84:87]
	v_mfma_f32_16x16x32_bf16 v[80:83], v[178:181], v[202:205], v[80:83]
	v_mfma_f32_16x16x32_bf16 v[68:71], v[170:173], v[210:213], v[68:71]
	v_mfma_f32_16x16x32_bf16 v[64:67], v[178:181], v[210:213], v[64:67]
	s_barrier
	s_add_i32 s30, s56, s23
	v_lshl_add_u64 v[182:183], v[214:215], 0, s[16:17]
	s_mov_b32 m0, s30
	s_nop 0
	global_load_lds_dwordx4 v[182:183], off
	s_add_i32 m0, s30, 0x2000
	s_add_u32 s30, s36, 0x160080
	v_lshl_add_u64 v[182:183], v[216:217], 0, s[16:17]
	s_addc_u32 s31, s37, 0
	s_add_i32 s36, s57, s23
	global_load_lds_dwordx4 v[182:183], off
	v_lshl_add_u64 v[182:183], s[30:31], 0, v[130:131]
	s_mov_b32 m0, s36
	s_nop 0
	global_load_lds_dwordx4 v[182:183], off
	v_lshl_add_u64 v[182:183], s[30:31], 0, v[134:135]
	s_add_i32 m0, s36, 0x2000
	s_nop 0
	global_load_lds_dwordx4 v[182:183], off
	v_lshl_add_u64 v[182:183], v[218:219], 0, s[16:17]
	s_mov_b32 m0, s45
	s_nop 0
	global_load_lds_dwordx4 v[182:183], off
	v_lshl_add_u64 v[182:183], v[220:221], 0, s[16:17]
	s_mov_b32 m0, s46
	s_nop 0
	global_load_lds_dwordx4 v[182:183], off
	ds_read_b128 v[182:185], v153 offset:49152
	ds_read_b128 v[186:189], v153 offset:50176
	ds_read_b128 v[190:193], v153 offset:51200
	ds_read_b128 v[194:197], v153 offset:52224
	ds_read_b128 v[198:201], v153 offset:53248
	ds_read_b128 v[202:205], v153 offset:54272
	ds_read_b128 v[206:209], v153 offset:55296
	ds_read_b128 v[210:213], v153 offset:56320
	s_waitcnt vmcnt(8)
	s_waitcnt lgkmcnt(0)
	s_barrier
	s_waitcnt lgkmcnt(0)
	v_mfma_f32_16x16x32_bf16 v[60:63], v[144:147], v[182:185], v[60:63]
	v_mfma_f32_16x16x32_bf16 v[56:59], v[158:161], v[182:185], v[56:59]
	v_mfma_f32_16x16x32_bf16 v[44:47], v[144:147], v[190:193], v[44:47]
	v_mfma_f32_16x16x32_bf16 v[40:43], v[158:161], v[190:193], v[40:43]
	v_mfma_f32_16x16x32_bf16 v[28:31], v[144:147], v[198:201], v[28:31]
	v_mfma_f32_16x16x32_bf16 v[24:27], v[158:161], v[198:201], v[24:27]
	v_mfma_f32_16x16x32_bf16 v[12:15], v[144:147], v[206:209], v[12:15]
	v_mfma_f32_16x16x32_bf16 v[8:11], v[158:161], v[206:209], v[8:11]
	v_mfma_f32_16x16x32_bf16 v[60:63], v[154:157], v[186:189], v[60:63]
	v_mfma_f32_16x16x32_bf16 v[56:59], v[162:165], v[186:189], v[56:59]
	v_mfma_f32_16x16x32_bf16 v[44:47], v[154:157], v[194:197], v[44:47]
	v_mfma_f32_16x16x32_bf16 v[40:43], v[162:165], v[194:197], v[40:43]
	v_mfma_f32_16x16x32_bf16 v[28:31], v[154:157], v[202:205], v[28:31]
	v_mfma_f32_16x16x32_bf16 v[24:27], v[162:165], v[202:205], v[24:27]
	v_mfma_f32_16x16x32_bf16 v[12:15], v[154:157], v[210:213], v[12:15]
	v_mfma_f32_16x16x32_bf16 v[8:11], v[162:165], v[210:213], v[8:11]
	v_mfma_f32_16x16x32_bf16 v[52:55], v[166:169], v[182:185], v[52:55]
	v_mfma_f32_16x16x32_bf16 v[48:51], v[174:177], v[182:185], v[48:51]
	v_mfma_f32_16x16x32_bf16 v[36:39], v[166:169], v[190:193], v[36:39]
	v_mfma_f32_16x16x32_bf16 v[32:35], v[174:177], v[190:193], v[32:35]
	v_mfma_f32_16x16x32_bf16 v[20:23], v[166:169], v[198:201], v[20:23]
	v_mfma_f32_16x16x32_bf16 v[16:19], v[174:177], v[198:201], v[16:19]
	v_mfma_f32_16x16x32_bf16 v[4:7], v[166:169], v[206:209], v[4:7]
	v_mfma_f32_16x16x32_bf16 v[0:3], v[174:177], v[206:209], v[0:3]
	v_mfma_f32_16x16x32_bf16 v[52:55], v[170:173], v[186:189], v[52:55]
	v_mfma_f32_16x16x32_bf16 v[48:51], v[178:181], v[186:189], v[48:51]
	v_mfma_f32_16x16x32_bf16 v[36:39], v[170:173], v[194:197], v[36:39]
	v_mfma_f32_16x16x32_bf16 v[32:35], v[178:181], v[194:197], v[32:35]
	v_mfma_f32_16x16x32_bf16 v[20:23], v[170:173], v[202:205], v[20:23]
	v_mfma_f32_16x16x32_bf16 v[16:19], v[178:181], v[202:205], v[16:19]
	v_mfma_f32_16x16x32_bf16 v[4:7], v[170:173], v[210:213], v[4:7]
	v_mfma_f32_16x16x32_bf16 v[0:3], v[178:181], v[210:213], v[0:3]
	s_barrier
	s_add_i32 s55, s55, 2
	s_add_u32 s53, s53, 0x100
	s_addc_u32 s54, s54, 0
	s_cmpk_gt_u32 s55, 0x55
	s_mov_b64 s[30:31], s[34:35]
	s_cbranch_scc0 .LBB0_1327
	s_and_b64 vcc, exec, s[8:9]
	s_cbranch_vccz .LBB0_1330
	s_barrier
